# phase 0 token-row loop: hand-written rmsnorm row part, pointers from scalar loads, DPP wave sums, gains batched, next item prefetched under the dt part
# speedup vs baseline: 1.0907x; 1.0132x over previous
.LBB0_465:
	s_or_b64 exec, exec, s[0:1]
	v_readlane_b32 s0, v254, 56
	v_readlane_b32 s1, v254, 57
	s_waitcnt lgkmcnt(0)
	s_barrier
	s_load_dwordx2 s[18:19], s[0:1], 0x108
	v_readlane_b32 s0, v255, 2
	s_cmpk_gt_i32 s0, 0x24f
	v_ashrrev_i32_e32 v1, 4, v174
	v_readlane_b32 s1, v255, 3
	s_cbranch_scc1 .LBB0_506
	v_and_b32_e32 v2, 64, v230
	v_add_u32_e32 v2, 64, v2
	v_xor_b32_e32 v3, 1, v230
	v_cmp_lt_i32_e32 vcc, v3, v2
	v_and_b32_e32 v4, 63, v174
	v_readlane_b32 s0, v254, 56
	v_cndmask_b32_e32 v3, v230, v3, vcc
	v_lshlrev_b32_e32 v27, 2, v3
	v_xor_b32_e32 v3, 2, v230
	v_cmp_lt_i32_e32 vcc, v3, v2
	v_readlane_b32 s1, v254, 57
	s_add_u32 s22, s0, 8
	v_cndmask_b32_e32 v3, v230, v3, vcc
	s_waitcnt vmcnt(0)
	v_lshlrev_b32_e32 v112, 2, v3
	v_xor_b32_e32 v3, 4, v230
	v_cmp_lt_i32_e32 vcc, v3, v2
	s_addc_u32 s23, s1, 0
	v_lshlrev_b32_e32 v68, 2, v4
	v_cndmask_b32_e32 v3, v230, v3, vcc
	v_lshlrev_b32_e32 v113, 2, v3
	v_xor_b32_e32 v3, 8, v230
	v_cmp_lt_i32_e32 vcc, v3, v2
	v_mov_b32_e32 v69, v26
	s_add_u32 s24, s0, 16
	v_cndmask_b32_e32 v3, v230, v3, vcc
	v_lshlrev_b32_e32 v114, 2, v3
	v_xor_b32_e32 v3, 16, v230
	v_cmp_lt_i32_e32 vcc, v3, v2
	v_readlane_b32 s0, v254, 11
	s_addc_u32 s25, s1, 0
	v_cndmask_b32_e32 v3, v230, v3, vcc
	v_lshlrev_b32_e32 v115, 2, v3
	v_xor_b32_e32 v3, 32, v230
	v_cmp_lt_i32_e32 vcc, v3, v2
	v_lshl_add_u32 v117, v4, 4, s0
	s_mov_b64 s[0:1], 0x5100000
	v_cndmask_b32_e32 v2, v230, v3, vcc
	v_lshlrev_b32_e32 v116, 2, v2
	v_lshlrev_b32_e32 v2, 3, v4
	v_mov_b32_e32 v3, v26
	s_waitcnt lgkmcnt(0)
	v_lshl_add_u64 v[70:71], s[18:19], 0, v[2:3]
	v_and_b32_e32 v3, 32, v174
	v_cmp_eq_u32_e32 vcc, 0, v3
	v_and_b32_e32 v3, 16, v174
	v_lshl_add_u64 v[4:5], s[18:19], 0, v[68:69]
	v_cmp_eq_u32_e64 s[4:5], 0, v3
	v_and_b32_e32 v3, 8, v174
	v_lshl_add_u64 v[72:73], v[4:5], 0, s[0:1]
	v_cmp_eq_u32_e64 s[6:7], 0, v3
	v_and_b32_e32 v3, 4, v174
	v_readlane_b32 s0, v255, 2
	v_cmp_eq_u32_e64 s[8:9], 0, v3
	v_and_b32_e32 v3, 2, v174
	v_readlane_b32 s1, v255, 3
	v_and_b32_e32 v6, -4, v1
	v_and_b32_e32 v2, 15, v174
	v_cmp_eq_u32_e64 s[10:11], 0, v3
	v_and_b32_e32 v3, 1, v174
	s_mov_b32 s2, s0
	v_readlane_b32 s0, v254, 62
	v_cmp_eq_u32_e64 s[12:13], 0, v3
	v_lshl_add_u32 v74, s2, 5, v6
	s_lshl_b32 s28, s0, 5
	v_lshlrev_b32_e32 v69, 2, v2
	s_mov_b32 s29, s2
	v_readlane_b32 s1, v254, 63
	v_readlane_b32 s14, v254, 56
	v_readlane_b32 s15, v254, 57
	v_lshlrev_b32_e32 v158, 2, v68
	v_mov_b32_e32 v159, v26
	s_nop 1
	s_load_dwordx4 s[0:3], s[14:15], 0x0
	s_load_dwordx2 s[26:27], s[14:15], 0x10
	s_load_dwordx2 s[30:31], s[14:15], 0x48
	s_load_dwordx2 s[14:15], s[14:15], 0xa8
	s_waitcnt lgkmcnt(0)
	v_lshl_add_u64 v[248:249], s[0:1], 0, v[158:159]
	v_lshl_add_u64 v[250:251], s[2:3], 0, v[158:159]
	v_lshl_add_u64 v[252:253], s[26:27], 0, v[158:159]
	v_lshl_add_u64 v[226:227], s[30:31], 0, v[158:159]
	v_lshl_add_u64 v[170:171], s[14:15], 0, v[158:159]
	v_cmp_lt_i32_e64 s[2:3], s49, v74
	s_movk_i32 s26, 0x3fff
	v_cmp_lt_i32_e64 s[26:27], s26, v74
	v_add_u32_e32 v160, 0xffffc000, v74
	v_add_u32_e32 v161, 0xffffbe00, v74
	v_mov_b32_e32 v164, 0x1000
	v_cndmask_b32_e64 v162, v248, v250, s[26:27]
	v_cndmask_b32_e64 v163, v249, v251, s[26:27]
	v_cndmask_b32_e64 v160, v74, v160, s[26:27]
	v_cndmask_b32_e64 v162, v162, v252, s[2:3]
	v_cndmask_b32_e64 v163, v163, v253, s[2:3]
	v_cndmask_b32_e64 v160, v160, v161, s[2:3]
	v_mov_b32_e32 v166, 0x3000
	v_lshl_add_u32 v164, v160, 12, v164
	v_lshl_add_u32 v166, v160, 12, v166
	v_mov_b32_e32 v165, v26
	v_mov_b32_e32 v167, v26
	v_lshl_add_u64 v[164:165], v[162:163], 0, v[164:165]
	v_lshl_add_u64 v[166:167], v[162:163], 0, v[166:167]
	global_load_dwordx4 v[178:181], v[164:165], off offset:-4096 nt
	global_load_dwordx4 v[182:185], v[164:165], off offset:-3072 nt
	global_load_dwordx4 v[186:189], v[164:165], off offset:-2048 nt
	global_load_dwordx4 v[190:193], v[164:165], off offset:-1024 nt
	global_load_dwordx4 v[194:197], v[164:165], off nt
	global_load_dwordx4 v[198:201], v[164:165], off offset:1024 nt
	global_load_dwordx4 v[202:205], v[164:165], off offset:2048 nt
	global_load_dwordx4 v[206:209], v[164:165], off offset:3072 nt
	global_load_dwordx4 v[210:213], v[166:167], off offset:-4096 nt
	global_load_dwordx4 v[214:217], v[166:167], off offset:-3072 nt
	global_load_dwordx4 v[218:221], v[166:167], off offset:-2048 nt
	global_load_dwordx4 v[222:225], v[166:167], off offset:-1024 nt
	global_load_dwordx4 v[232:235], v[166:167], off nt
	global_load_dwordx4 v[236:239], v[166:167], off offset:1024 nt
	global_load_dwordx4 v[240:243], v[166:167], off offset:2048 nt
	global_load_dwordx4 v[244:247], v[166:167], off offset:3072 nt
	s_mov_b32 s30, 0
	s_branch .LBB0_469
.LBB0_467:
	s_mov_b32 s30, 1
	s_or_b64 exec, exec, s[0:1]
	v_max_f32_e32 v2, v2, v2
	v_max_f32_e32 v2, 0, v2
	v_ashrrev_i32_e32 v75, 31, v74
	v_add_f32_e32 v4, v2, v3
	v_lshlrev_b64 v[2:3], 6, v[74:75]
	v_lshl_add_u64 v[2:3], v[72:73], 0, v[2:3]
	global_store_dword v[2:3], v4, off

.LBB0_469:
	v_cmp_lt_i32_e64 s[2:3], s49, v74
	v_cmp_gt_i32_e64 s[0:1], s55, v74
	v_add_u32_e32 v159, 0xffffbe00, v74
	v_mov_b32_e32 v162, 0x4501000
	v_mov_b32_e32 v161, 0x2401000
	v_cndmask_b32_e64 v168, v226, v170, s[2:3]
	v_cndmask_b32_e64 v169, v227, v171, s[2:3]
	v_cndmask_b32_e64 v159, v74, v159, s[2:3]
	v_cndmask_b32_e64 v161, v161, v162, s[2:3]
	global_load_dwordx4 v[2:5], v[168:169], off
	global_load_dwordx4 v[6:9], v[168:169], off offset:1024
	global_load_dwordx4 v[10:13], v[168:169], off offset:2048
	global_load_dwordx4 v[14:17], v[168:169], off offset:3072
	v_lshl_add_u32 v160, v159, 11, v161
	v_mov_b32_e32 v161, v26
	v_mov_b32_e32 v162, 0x3a800000
	v_lshl_add_u64 v[160:161], v[70:71], 0, v[160:161]
	s_cmp_lg_u32 s30, 0
	s_cbranch_scc1 .Lrow_xready
	s_waitcnt vmcnt(4)
.Lrow_xready:
	v_pk_mul_f32 v[58:59], v[178:179], v[178:179]
	v_pk_mul_f32 v[60:61], v[194:195], v[194:195]
	v_pk_mul_f32 v[62:63], v[210:211], v[210:211]
	v_pk_mul_f32 v[64:65], v[232:233], v[232:233]
	v_pk_fma_f32 v[58:59], v[180:181], v[180:181], v[58:59]
	v_pk_fma_f32 v[60:61], v[196:197], v[196:197], v[60:61]
	v_pk_fma_f32 v[62:63], v[212:213], v[212:213], v[62:63]
	v_pk_fma_f32 v[64:65], v[234:235], v[234:235], v[64:65]
	v_pk_fma_f32 v[58:59], v[182:183], v[182:183], v[58:59]
	v_pk_fma_f32 v[60:61], v[198:199], v[198:199], v[60:61]
	v_pk_fma_f32 v[62:63], v[214:215], v[214:215], v[62:63]
	v_pk_fma_f32 v[64:65], v[236:237], v[236:237], v[64:65]
	v_pk_fma_f32 v[58:59], v[184:185], v[184:185], v[58:59]
	v_pk_fma_f32 v[60:61], v[200:201], v[200:201], v[60:61]
	v_pk_fma_f32 v[62:63], v[216:217], v[216:217], v[62:63]
	v_pk_fma_f32 v[64:65], v[238:239], v[238:239], v[64:65]
	v_pk_fma_f32 v[58:59], v[186:187], v[186:187], v[58:59]
	v_pk_fma_f32 v[60:61], v[202:203], v[202:203], v[60:61]
	v_pk_fma_f32 v[62:63], v[218:219], v[218:219], v[62:63]
	v_pk_fma_f32 v[64:65], v[240:241], v[240:241], v[64:65]
	v_pk_fma_f32 v[58:59], v[188:189], v[188:189], v[58:59]
	v_pk_fma_f32 v[60:61], v[204:205], v[204:205], v[60:61]
	v_pk_fma_f32 v[62:63], v[220:221], v[220:221], v[62:63]
	v_pk_fma_f32 v[64:65], v[242:243], v[242:243], v[64:65]
	v_pk_fma_f32 v[58:59], v[190:191], v[190:191], v[58:59]
	v_pk_fma_f32 v[60:61], v[206:207], v[206:207], v[60:61]
	v_pk_fma_f32 v[62:63], v[222:223], v[222:223], v[62:63]
	v_pk_fma_f32 v[64:65], v[244:245], v[244:245], v[64:65]
	v_pk_fma_f32 v[58:59], v[192:193], v[192:193], v[58:59]
	v_pk_fma_f32 v[60:61], v[208:209], v[208:209], v[60:61]
	v_pk_fma_f32 v[62:63], v[224:225], v[224:225], v[62:63]
	v_pk_fma_f32 v[64:65], v[246:247], v[246:247], v[64:65]
	v_add_f32_e32 v58, v58, v59
	v_add_f32_e32 v60, v60, v61
	v_add_f32_e32 v62, v62, v63
	v_add_f32_e32 v64, v64, v65
	v_add_f32_dpp v58, v58, v58 quad_perm:[1,0,3,2] row_mask:0xf bank_mask:0xf
	v_add_f32_dpp v60, v60, v60 quad_perm:[1,0,3,2] row_mask:0xf bank_mask:0xf
	v_add_f32_dpp v62, v62, v62 quad_perm:[1,0,3,2] row_mask:0xf bank_mask:0xf
	v_add_f32_dpp v64, v64, v64 quad_perm:[1,0,3,2] row_mask:0xf bank_mask:0xf
	v_add_f32_dpp v58, v58, v58 quad_perm:[2,3,0,1] row_mask:0xf bank_mask:0xf
	v_add_f32_dpp v60, v60, v60 quad_perm:[2,3,0,1] row_mask:0xf bank_mask:0xf
	v_add_f32_dpp v62, v62, v62 quad_perm:[2,3,0,1] row_mask:0xf bank_mask:0xf
	v_add_f32_dpp v64, v64, v64 quad_perm:[2,3,0,1] row_mask:0xf bank_mask:0xf
	v_add_f32_dpp v58, v58, v58 row_half_mirror row_mask:0xf bank_mask:0xf
	v_add_f32_dpp v60, v60, v60 row_half_mirror row_mask:0xf bank_mask:0xf
	v_add_f32_dpp v62, v62, v62 row_half_mirror row_mask:0xf bank_mask:0xf
	v_add_f32_dpp v64, v64, v64 row_half_mirror row_mask:0xf bank_mask:0xf
	v_add_f32_dpp v58, v58, v58 row_mirror row_mask:0xf bank_mask:0xf
	v_add_f32_dpp v60, v60, v60 row_mirror row_mask:0xf bank_mask:0xf
	v_add_f32_dpp v62, v62, v62 row_mirror row_mask:0xf bank_mask:0xf
	v_add_f32_dpp v64, v64, v64 row_mirror row_mask:0xf bank_mask:0xf
	v_add_f32_dpp v58, v58, v58 row_bcast:15 row_mask:0xa bank_mask:0xf
	v_add_f32_dpp v60, v60, v60 row_bcast:15 row_mask:0xa bank_mask:0xf
	v_add_f32_dpp v62, v62, v62 row_bcast:15 row_mask:0xa bank_mask:0xf
	v_add_f32_dpp v64, v64, v64 row_bcast:15 row_mask:0xa bank_mask:0xf
	v_add_f32_dpp v58, v58, v58 row_bcast:31 row_mask:0xc bank_mask:0xf
	v_add_f32_dpp v60, v60, v60 row_bcast:31 row_mask:0xc bank_mask:0xf
	v_add_f32_dpp v62, v62, v62 row_bcast:31 row_mask:0xc bank_mask:0xf
	v_add_f32_dpp v64, v64, v64 row_bcast:31 row_mask:0xc bank_mask:0xf
	s_nop 1
	v_readlane_b32 s22, v58, 63
	v_readlane_b32 s23, v60, 63
	v_readlane_b32 s24, v62, 63
	v_readlane_b32 s25, v64, 63
	s_nop 1
	v_fma_f32 v104, s22, v162, v172
	v_fma_f32 v106, s23, v162, v172
	v_fma_f32 v108, s24, v162, v172
	v_fma_f32 v110, s25, v162, v172
	v_rsq_f32_e32 v104, v104
	v_rsq_f32_e32 v106, v106
	v_rsq_f32_e32 v108, v108
	v_rsq_f32_e32 v110, v110
	s_waitcnt vmcnt(0)
	v_pk_mul_f32 v[178:179], v[178:179], v[104:105] op_sel_hi:[1,0]
	v_pk_mul_f32 v[180:181], v[180:181], v[104:105] op_sel_hi:[1,0]
	v_pk_mul_f32 v[182:183], v[182:183], v[104:105] op_sel_hi:[1,0]
	v_pk_mul_f32 v[184:185], v[184:185], v[104:105] op_sel_hi:[1,0]
	v_pk_mul_f32 v[186:187], v[186:187], v[104:105] op_sel_hi:[1,0]
	v_pk_mul_f32 v[188:189], v[188:189], v[104:105] op_sel_hi:[1,0]
	v_pk_mul_f32 v[190:191], v[190:191], v[104:105] op_sel_hi:[1,0]
	v_pk_mul_f32 v[192:193], v[192:193], v[104:105] op_sel_hi:[1,0]
	v_pk_mul_f32 v[90:91], v[2:3], v[178:179]
	v_pk_mul_f32 v[82:83], v[4:5], v[180:181]
	v_pk_mul_f32 v[88:89], v[6:7], v[182:183]
	v_pk_mul_f32 v[80:81], v[8:9], v[184:185]
	v_pk_mul_f32 v[86:87], v[10:11], v[186:187]
	v_pk_mul_f32 v[78:79], v[12:13], v[188:189]
	v_pk_mul_f32 v[84:85], v[14:15], v[190:191]
	v_pk_mul_f32 v[76:77], v[16:17], v[192:193]
	v_cvt_pk_bf16_f32 v178, v90, v91
	v_cvt_pk_bf16_f32 v179, v82, v83
	v_cvt_pk_bf16_f32 v182, v88, v89
	v_cvt_pk_bf16_f32 v183, v80, v81
	v_cvt_pk_bf16_f32 v186, v86, v87
	v_cvt_pk_bf16_f32 v187, v78, v79
	v_cvt_pk_bf16_f32 v190, v84, v85
	v_cvt_pk_bf16_f32 v191, v76, v77
	global_store_dwordx2 v[160:161], v[178:179], off offset:-4096
	global_store_dwordx2 v[160:161], v[182:183], off offset:-3584
	global_store_dwordx2 v[160:161], v[186:187], off offset:-3072
	global_store_dwordx2 v[160:161], v[190:191], off offset:-2560
	v_pk_mul_f32 v[194:195], v[194:195], v[106:107] op_sel_hi:[1,0]
	v_pk_mul_f32 v[196:197], v[196:197], v[106:107] op_sel_hi:[1,0]
	v_pk_mul_f32 v[198:199], v[198:199], v[106:107] op_sel_hi:[1,0]
	v_pk_mul_f32 v[200:201], v[200:201], v[106:107] op_sel_hi:[1,0]
	v_pk_mul_f32 v[202:203], v[202:203], v[106:107] op_sel_hi:[1,0]
	v_pk_mul_f32 v[204:205], v[204:205], v[106:107] op_sel_hi:[1,0]
	v_pk_mul_f32 v[206:207], v[206:207], v[106:107] op_sel_hi:[1,0]
	v_pk_mul_f32 v[208:209], v[208:209], v[106:107] op_sel_hi:[1,0]
	v_pk_mul_f32 v[102:103], v[2:3], v[194:195]
	v_pk_mul_f32 v[96:97], v[4:5], v[196:197]
	v_pk_mul_f32 v[100:101], v[6:7], v[198:199]
	v_pk_mul_f32 v[94:95], v[8:9], v[200:201]
	v_pk_mul_f32 v[98:99], v[10:11], v[202:203]
	v_pk_mul_f32 v[92:93], v[12:13], v[204:205]
	v_pk_mul_f32 v[20:21], v[14:15], v[206:207]
	v_pk_mul_f32 v[18:19], v[16:17], v[208:209]
	v_cvt_pk_bf16_f32 v194, v102, v103
	v_cvt_pk_bf16_f32 v195, v96, v97
	v_cvt_pk_bf16_f32 v198, v100, v101
	v_cvt_pk_bf16_f32 v199, v94, v95
	v_cvt_pk_bf16_f32 v202, v98, v99
	v_cvt_pk_bf16_f32 v203, v92, v93
	v_cvt_pk_bf16_f32 v206, v20, v21
	v_cvt_pk_bf16_f32 v207, v18, v19
	global_store_dwordx2 v[160:161], v[194:195], off offset:-2048
	global_store_dwordx2 v[160:161], v[198:199], off offset:-1536
	global_store_dwordx2 v[160:161], v[202:203], off offset:-1024
	global_store_dwordx2 v[160:161], v[206:207], off offset:-512
	v_pk_mul_f32 v[210:211], v[210:211], v[108:109] op_sel_hi:[1,0]
	v_pk_mul_f32 v[212:213], v[212:213], v[108:109] op_sel_hi:[1,0]
	v_pk_mul_f32 v[214:215], v[214:215], v[108:109] op_sel_hi:[1,0]
	v_pk_mul_f32 v[216:217], v[216:217], v[108:109] op_sel_hi:[1,0]
	v_pk_mul_f32 v[218:219], v[218:219], v[108:109] op_sel_hi:[1,0]
	v_pk_mul_f32 v[220:221], v[220:221], v[108:109] op_sel_hi:[1,0]
	v_pk_mul_f32 v[222:223], v[222:223], v[108:109] op_sel_hi:[1,0]
	v_pk_mul_f32 v[224:225], v[224:225], v[108:109] op_sel_hi:[1,0]
	v_pk_mul_f32 v[34:35], v[2:3], v[210:211]
	v_pk_mul_f32 v[28:29], v[4:5], v[212:213]
	v_pk_mul_f32 v[40:41], v[6:7], v[214:215]
	v_pk_mul_f32 v[30:31], v[8:9], v[216:217]
	v_pk_mul_f32 v[36:37], v[10:11], v[218:219]
	v_pk_mul_f32 v[32:33], v[12:13], v[220:221]
	v_pk_mul_f32 v[24:25], v[14:15], v[222:223]
	v_pk_mul_f32 v[22:23], v[16:17], v[224:225]
	v_cvt_pk_bf16_f32 v210, v34, v35
	v_cvt_pk_bf16_f32 v211, v28, v29
	v_cvt_pk_bf16_f32 v214, v40, v41
	v_cvt_pk_bf16_f32 v215, v30, v31
	v_cvt_pk_bf16_f32 v218, v36, v37
	v_cvt_pk_bf16_f32 v219, v32, v33
	v_cvt_pk_bf16_f32 v222, v24, v25
	v_cvt_pk_bf16_f32 v223, v22, v23
	global_store_dwordx2 v[160:161], v[210:211], off
	global_store_dwordx2 v[160:161], v[214:215], off offset:512
	global_store_dwordx2 v[160:161], v[218:219], off offset:1024
	global_store_dwordx2 v[160:161], v[222:223], off offset:1536
	v_pk_mul_f32 v[232:233], v[232:233], v[110:111] op_sel_hi:[1,0]
	v_pk_mul_f32 v[234:235], v[234:235], v[110:111] op_sel_hi:[1,0]
	v_pk_mul_f32 v[236:237], v[236:237], v[110:111] op_sel_hi:[1,0]
	v_pk_mul_f32 v[238:239], v[238:239], v[110:111] op_sel_hi:[1,0]
	v_pk_mul_f32 v[240:241], v[240:241], v[110:111] op_sel_hi:[1,0]
	v_pk_mul_f32 v[242:243], v[242:243], v[110:111] op_sel_hi:[1,0]
	v_pk_mul_f32 v[244:245], v[244:245], v[110:111] op_sel_hi:[1,0]
	v_pk_mul_f32 v[246:247], v[246:247], v[110:111] op_sel_hi:[1,0]
	v_pk_mul_f32 v[42:43], v[2:3], v[232:233]
	v_pk_mul_f32 v[38:39], v[4:5], v[234:235]
	v_pk_mul_f32 v[48:49], v[6:7], v[236:237]
	v_pk_mul_f32 v[44:45], v[8:9], v[238:239]
	v_pk_mul_f32 v[56:57], v[10:11], v[240:241]
	v_pk_mul_f32 v[50:51], v[12:13], v[242:243]
	v_pk_mul_f32 v[52:53], v[14:15], v[244:245]
	v_pk_mul_f32 v[46:47], v[16:17], v[246:247]
	v_cvt_pk_bf16_f32 v232, v42, v43
	v_cvt_pk_bf16_f32 v233, v38, v39
	v_cvt_pk_bf16_f32 v236, v48, v49
	v_cvt_pk_bf16_f32 v237, v44, v45
	v_cvt_pk_bf16_f32 v240, v56, v57
	v_cvt_pk_bf16_f32 v241, v50, v51
	v_cvt_pk_bf16_f32 v244, v52, v53
	v_cvt_pk_bf16_f32 v245, v46, v47
	global_store_dwordx2 v[160:161], v[232:233], off offset:2048
	global_store_dwordx2 v[160:161], v[236:237], off offset:2560
	global_store_dwordx2 v[160:161], v[240:241], off offset:3072
	global_store_dwordx2 v[160:161], v[244:245], off offset:3584
	v_readlane_b32 s30, v254, 62
	s_add_i32 s30, s29, s30
	s_cmpk_gt_i32 s30, 0x24f
	s_cbranch_scc1 .Lrow_nopf
	v_add_u32_e32 v159, s28, v74
	v_cmp_lt_i32_e64 s[2:3], s49, v159
	s_movk_i32 s26, 0x3fff
	v_cmp_lt_i32_e64 s[26:27], s26, v159
	v_add_u32_e32 v160, 0xffffc000, v159
	v_add_u32_e32 v161, 0xffffbe00, v159
	v_mov_b32_e32 v164, 0x1000
	v_cndmask_b32_e64 v162, v248, v250, s[26:27]
	v_cndmask_b32_e64 v163, v249, v251, s[26:27]
	v_cndmask_b32_e64 v160, v159, v160, s[26:27]
	v_cndmask_b32_e64 v162, v162, v252, s[2:3]
	v_cndmask_b32_e64 v163, v163, v253, s[2:3]
	v_cndmask_b32_e64 v160, v160, v161, s[2:3]
	v_mov_b32_e32 v166, 0x3000
	v_lshl_add_u32 v164, v160, 12, v164
	v_lshl_add_u32 v166, v160, 12, v166
	v_mov_b32_e32 v165, v26
	v_mov_b32_e32 v167, v26
	v_lshl_add_u64 v[164:165], v[162:163], 0, v[164:165]
	v_lshl_add_u64 v[166:167], v[162:163], 0, v[166:167]
	global_load_dwordx4 v[178:181], v[164:165], off offset:-4096 nt
	global_load_dwordx4 v[182:185], v[164:165], off offset:-3072 nt
	global_load_dwordx4 v[186:189], v[164:165], off offset:-2048 nt
	global_load_dwordx4 v[190:193], v[164:165], off offset:-1024 nt
	global_load_dwordx4 v[194:197], v[164:165], off nt
	global_load_dwordx4 v[198:201], v[164:165], off offset:1024 nt
	global_load_dwordx4 v[202:205], v[164:165], off offset:2048 nt
	global_load_dwordx4 v[206:209], v[164:165], off offset:3072 nt
	global_load_dwordx4 v[210:213], v[166:167], off offset:-4096 nt
	global_load_dwordx4 v[214:217], v[166:167], off offset:-3072 nt
	global_load_dwordx4 v[218:221], v[166:167], off offset:-2048 nt
	global_load_dwordx4 v[222:225], v[166:167], off offset:-1024 nt
	global_load_dwordx4 v[232:235], v[166:167], off nt
	global_load_dwordx4 v[236:239], v[166:167], off offset:1024 nt
	global_load_dwordx4 v[240:243], v[166:167], off offset:2048 nt
	global_load_dwordx4 v[244:247], v[166:167], off offset:3072 nt
.Lrow_nopf:
	s_mov_b32 s30, 0
	s_and_saveexec_b64 s[14:15], s[0:1]
	s_cbranch_execz .LBB0_468
	ds_read_b128 v[2:5], v117
	ds_read_b128 v[6:9], v117 offset:1024
	ds_read_b128 v[10:13], v117 offset:2048
	ds_read_b128 v[14:17], v117 offset:3072
	v_readlane_b32 s0, v254, 56
	s_waitcnt lgkmcnt(3)
	v_mul_f32_e32 v54, v91, v3
	s_waitcnt lgkmcnt(2)
	v_mul_f32_e32 v55, v89, v7
	v_fmac_f32_e32 v54, v90, v2
	v_fmac_f32_e32 v54, v82, v4
	v_fmac_f32_e32 v55, v88, v6
	v_fmac_f32_e32 v54, v83, v5
	v_fmac_f32_e32 v55, v80, v8
	v_add_f32_e32 v54, 0, v54
	v_fmac_f32_e32 v55, v81, v9
	v_add_f32_e32 v54, v54, v55
	s_waitcnt lgkmcnt(1)
	v_mul_f32_e32 v55, v87, v11
	v_fmac_f32_e32 v55, v86, v10
	v_fmac_f32_e32 v55, v78, v12
	v_fmac_f32_e32 v55, v79, v13
	v_add_f32_e32 v54, v54, v55
	s_waitcnt lgkmcnt(0)
	v_mul_f32_e32 v55, v85, v15
	v_fmac_f32_e32 v55, v84, v14
	v_fmac_f32_e32 v55, v76, v16
	v_fmac_f32_e32 v55, v77, v17
	v_add_f32_e32 v59, v54, v55
	v_mul_f32_e32 v54, v103, v3
	v_fmac_f32_e32 v54, v102, v2
	v_mul_f32_e32 v55, v101, v7
	v_fmac_f32_e32 v54, v96, v4
	v_fmac_f32_e32 v55, v100, v6
	v_fmac_f32_e32 v54, v97, v5
	v_fmac_f32_e32 v55, v94, v8
	v_add_f32_e32 v54, 0, v54
	v_fmac_f32_e32 v55, v95, v9
	v_add_f32_e32 v54, v54, v55
	v_mul_f32_e32 v55, v99, v11
	v_fmac_f32_e32 v55, v98, v10
	v_fmac_f32_e32 v55, v92, v12
	v_fmac_f32_e32 v55, v93, v13
	v_add_f32_e32 v54, v54, v55
	v_mul_f32_e32 v55, v21, v15
	v_fmac_f32_e32 v55, v20, v14
	v_fmac_f32_e32 v55, v18, v16
	v_fmac_f32_e32 v55, v19, v17
	v_add_f32_e32 v54, v54, v55
	v_mul_f32_e32 v55, v35, v3
	v_mul_f32_e32 v3, v43, v3
	v_fmac_f32_e32 v3, v42, v2
	v_fmac_f32_e32 v3, v38, v4
	v_fmac_f32_e32 v55, v34, v2
	v_mul_f32_e32 v58, v41, v7
	v_fmac_f32_e32 v3, v39, v5
	v_fmac_f32_e32 v55, v28, v4
	v_fmac_f32_e32 v58, v40, v6
	v_add_f32_e32 v2, 0, v3
	v_mul_f32_e32 v3, v49, v7
	v_fmac_f32_e32 v55, v29, v5
	v_fmac_f32_e32 v58, v30, v8
	v_fmac_f32_e32 v3, v48, v6
	v_add_f32_e32 v55, 0, v55
	v_fmac_f32_e32 v58, v31, v9
	v_fmac_f32_e32 v3, v44, v8
	v_add_f32_e32 v55, v55, v58
	v_mul_f32_e32 v58, v37, v11
	v_fmac_f32_e32 v3, v45, v9
	v_fmac_f32_e32 v58, v36, v10
	v_add_f32_e32 v2, v2, v3
	v_mul_f32_e32 v3, v57, v11
	v_fmac_f32_e32 v58, v32, v12
	v_fmac_f32_e32 v3, v56, v10
	v_fmac_f32_e32 v58, v33, v13
	v_fmac_f32_e32 v3, v50, v12
	v_add_f32_e32 v55, v55, v58
	v_mul_f32_e32 v58, v25, v15
	v_fmac_f32_e32 v3, v51, v13
	v_mul_f32_e32 v7, v53, v15
	v_fmac_f32_e32 v58, v24, v14
	v_add_f32_e32 v6, v2, v3
	v_fmac_f32_e32 v7, v52, v14
	ds_read_b128 v[2:5], v117 offset:4096
	v_fmac_f32_e32 v58, v22, v16
	v_fmac_f32_e32 v7, v46, v16
	v_fmac_f32_e32 v58, v23, v17
	v_fmac_f32_e32 v7, v47, v17
	v_add_f32_e32 v60, v55, v58
	v_add_f32_e32 v55, v6, v7
	ds_read_b128 v[6:9], v117 offset:5120
	ds_read_b128 v[10:13], v117 offset:6144
	ds_read_b128 v[14:17], v117 offset:7168
	s_waitcnt lgkmcnt(3)
	v_mul_f32_e32 v58, v91, v3
	v_fmac_f32_e32 v58, v90, v2
	s_waitcnt lgkmcnt(2)
	v_mul_f32_e32 v61, v89, v7
	v_fmac_f32_e32 v58, v82, v4
	v_fmac_f32_e32 v61, v88, v6
	v_fmac_f32_e32 v58, v83, v5
	v_fmac_f32_e32 v61, v80, v8
	v_add_f32_e32 v58, 0, v58
	v_fmac_f32_e32 v61, v81, v9
	v_add_f32_e32 v58, v58, v61
	s_waitcnt lgkmcnt(1)
	v_mul_f32_e32 v61, v87, v11
	v_fmac_f32_e32 v61, v86, v10
	v_fmac_f32_e32 v61, v78, v12
	v_fmac_f32_e32 v61, v79, v13
	v_add_f32_e32 v58, v58, v61
	s_waitcnt lgkmcnt(0)
	v_mul_f32_e32 v61, v85, v15
	v_fmac_f32_e32 v61, v84, v14
	v_fmac_f32_e32 v61, v76, v16
	v_fmac_f32_e32 v61, v77, v17
	v_add_f32_e32 v62, v58, v61
	v_mul_f32_e32 v58, v103, v3
	v_fmac_f32_e32 v58, v102, v2
	v_mul_f32_e32 v61, v101, v7
	v_fmac_f32_e32 v58, v96, v4
	v_fmac_f32_e32 v61, v100, v6
	v_fmac_f32_e32 v58, v97, v5
	v_fmac_f32_e32 v61, v94, v8
	v_add_f32_e32 v58, 0, v58
	v_fmac_f32_e32 v61, v95, v9
	v_add_f32_e32 v58, v58, v61
	v_mul_f32_e32 v61, v99, v11
	v_fmac_f32_e32 v61, v98, v10
	v_fmac_f32_e32 v61, v92, v12
	v_fmac_f32_e32 v61, v93, v13
	v_add_f32_e32 v58, v58, v61
	v_mul_f32_e32 v61, v21, v15
	v_fmac_f32_e32 v61, v20, v14
	v_fmac_f32_e32 v61, v18, v16
	v_fmac_f32_e32 v61, v19, v17
	v_add_f32_e32 v58, v58, v61
	v_mul_f32_e32 v61, v35, v3
	v_mul_f32_e32 v3, v43, v3
	v_fmac_f32_e32 v3, v42, v2
	v_fmac_f32_e32 v3, v38, v4
	v_fmac_f32_e32 v61, v34, v2
	v_mul_f32_e32 v63, v41, v7
	v_fmac_f32_e32 v3, v39, v5
	v_fmac_f32_e32 v61, v28, v4
	v_fmac_f32_e32 v63, v40, v6
	v_add_f32_e32 v2, 0, v3
	v_mul_f32_e32 v3, v49, v7
	v_fmac_f32_e32 v61, v29, v5
	v_fmac_f32_e32 v63, v30, v8
	v_fmac_f32_e32 v3, v48, v6
	v_add_f32_e32 v61, 0, v61
	v_fmac_f32_e32 v63, v31, v9
	v_fmac_f32_e32 v3, v44, v8
	v_add_f32_e32 v61, v61, v63
	v_mul_f32_e32 v63, v37, v11
	v_fmac_f32_e32 v3, v45, v9
	v_fmac_f32_e32 v63, v36, v10
	v_add_f32_e32 v2, v2, v3
	v_mul_f32_e32 v3, v57, v11
	v_fmac_f32_e32 v63, v32, v12
	v_fmac_f32_e32 v3, v56, v10
	v_fmac_f32_e32 v63, v33, v13
	v_fmac_f32_e32 v3, v50, v12
	v_add_f32_e32 v61, v61, v63
	v_mul_f32_e32 v63, v25, v15
	v_fmac_f32_e32 v3, v51, v13
	v_mul_f32_e32 v7, v53, v15
	v_fmac_f32_e32 v63, v24, v14
	v_add_f32_e32 v6, v2, v3
	v_fmac_f32_e32 v7, v52, v14
	ds_read_b128 v[2:5], v117 offset:8192
	v_fmac_f32_e32 v63, v22, v16
	v_fmac_f32_e32 v7, v46, v16
	v_fmac_f32_e32 v63, v23, v17
	v_fmac_f32_e32 v7, v47, v17
	v_add_f32_e32 v64, v61, v63
	v_add_f32_e32 v61, v6, v7
	ds_read_b128 v[6:9], v117 offset:9216
	ds_read_b128 v[10:13], v117 offset:10240
	ds_read_b128 v[14:17], v117 offset:11264
	s_waitcnt lgkmcnt(3)
	v_mul_f32_e32 v63, v91, v3
	v_fmac_f32_e32 v63, v90, v2
	s_waitcnt lgkmcnt(2)
	v_mul_f32_e32 v65, v89, v7
	v_fmac_f32_e32 v63, v82, v4
	v_fmac_f32_e32 v65, v88, v6
	v_fmac_f32_e32 v63, v83, v5
	v_fmac_f32_e32 v65, v80, v8
	v_add_f32_e32 v63, 0, v63
	v_fmac_f32_e32 v65, v81, v9
	v_add_f32_e32 v63, v63, v65
	s_waitcnt lgkmcnt(1)
	v_mul_f32_e32 v65, v87, v11
	v_fmac_f32_e32 v65, v86, v10
	v_fmac_f32_e32 v65, v78, v12
	v_fmac_f32_e32 v65, v79, v13
	v_add_f32_e32 v63, v63, v65
	s_waitcnt lgkmcnt(0)
	v_mul_f32_e32 v65, v85, v15
	v_fmac_f32_e32 v65, v84, v14
	v_fmac_f32_e32 v65, v76, v16
	v_fmac_f32_e32 v65, v77, v17
	v_add_f32_e32 v65, v63, v65
	v_mul_f32_e32 v63, v103, v3
	v_fmac_f32_e32 v63, v102, v2
	v_mul_f32_e32 v66, v101, v7
	v_fmac_f32_e32 v63, v96, v4
	v_fmac_f32_e32 v66, v100, v6
	v_fmac_f32_e32 v63, v97, v5
	v_fmac_f32_e32 v66, v94, v8
	v_add_f32_e32 v63, 0, v63
	v_fmac_f32_e32 v66, v95, v9
	v_add_f32_e32 v63, v63, v66
	v_mul_f32_e32 v66, v99, v11
	v_fmac_f32_e32 v66, v98, v10
	v_fmac_f32_e32 v66, v92, v12
	v_fmac_f32_e32 v66, v93, v13
	v_add_f32_e32 v63, v63, v66
	v_mul_f32_e32 v66, v21, v15
	v_fmac_f32_e32 v66, v20, v14
	v_fmac_f32_e32 v66, v18, v16
	v_fmac_f32_e32 v66, v19, v17
	v_add_f32_e32 v63, v63, v66
	v_mul_f32_e32 v66, v35, v3
	v_mul_f32_e32 v3, v43, v3
	v_fmac_f32_e32 v3, v42, v2
	v_fmac_f32_e32 v3, v38, v4
	v_fmac_f32_e32 v66, v34, v2
	v_mul_f32_e32 v67, v41, v7
	v_fmac_f32_e32 v3, v39, v5
	v_fmac_f32_e32 v66, v28, v4
	v_fmac_f32_e32 v67, v40, v6
	v_add_f32_e32 v2, 0, v3
	v_mul_f32_e32 v3, v49, v7
	v_fmac_f32_e32 v66, v29, v5
	v_fmac_f32_e32 v67, v30, v8
	v_fmac_f32_e32 v3, v48, v6
	v_add_f32_e32 v66, 0, v66
	v_fmac_f32_e32 v67, v31, v9
	v_fmac_f32_e32 v3, v44, v8
	v_add_f32_e32 v66, v66, v67
	v_mul_f32_e32 v67, v37, v11
	v_fmac_f32_e32 v3, v45, v9
	v_fmac_f32_e32 v67, v36, v10
	v_add_f32_e32 v2, v2, v3
	v_mul_f32_e32 v3, v57, v11
	v_fmac_f32_e32 v67, v32, v12
	v_fmac_f32_e32 v3, v56, v10
	v_fmac_f32_e32 v67, v33, v13
	v_fmac_f32_e32 v3, v50, v12
	v_add_f32_e32 v66, v66, v67
	v_mul_f32_e32 v67, v25, v15
	v_fmac_f32_e32 v3, v51, v13
	v_mul_f32_e32 v7, v53, v15
	v_fmac_f32_e32 v67, v24, v14
	v_add_f32_e32 v6, v2, v3
	v_fmac_f32_e32 v7, v52, v14
	ds_read_b128 v[2:5], v117 offset:12288
	v_fmac_f32_e32 v67, v22, v16
	v_fmac_f32_e32 v7, v46, v16
	v_fmac_f32_e32 v67, v23, v17
	v_fmac_f32_e32 v7, v47, v17
	v_add_f32_e32 v67, v66, v67
	v_add_f32_e32 v66, v6, v7
	ds_read_b128 v[6:9], v117 offset:13312
	ds_read_b128 v[10:13], v117 offset:14336
	ds_read_b128 v[14:17], v117 offset:15360
	s_waitcnt lgkmcnt(3)
	v_mul_f32_e32 v75, v91, v3
	v_fmac_f32_e32 v75, v90, v2
	s_waitcnt lgkmcnt(2)
	v_mul_f32_e32 v104, v89, v7
	v_fmac_f32_e32 v75, v82, v4
	v_fmac_f32_e32 v104, v88, v6
	v_fmac_f32_e32 v75, v83, v5
	v_fmac_f32_e32 v104, v80, v8
	v_add_f32_e32 v75, 0, v75
	v_fmac_f32_e32 v104, v81, v9
	v_add_f32_e32 v75, v75, v104
	s_waitcnt lgkmcnt(1)
	v_mul_f32_e32 v104, v87, v11
	v_fmac_f32_e32 v104, v86, v10
	v_fmac_f32_e32 v104, v78, v12
	v_fmac_f32_e32 v104, v79, v13
	v_add_f32_e32 v75, v75, v104
	s_waitcnt lgkmcnt(0)
	v_mul_f32_e32 v104, v85, v15
	v_fmac_f32_e32 v104, v84, v14
	v_fmac_f32_e32 v104, v76, v16
	v_fmac_f32_e32 v104, v77, v17
	v_add_f32_e32 v104, v75, v104
	v_mul_f32_e32 v75, v103, v3
	v_fmac_f32_e32 v75, v102, v2
	v_mul_f32_e32 v105, v101, v7
	v_fmac_f32_e32 v75, v96, v4
	v_fmac_f32_e32 v105, v100, v6
	v_fmac_f32_e32 v75, v97, v5
	v_fmac_f32_e32 v105, v94, v8
	v_add_f32_e32 v75, 0, v75
	v_fmac_f32_e32 v105, v95, v9
	v_add_f32_e32 v75, v75, v105
	v_mul_f32_e32 v105, v99, v11
	v_fmac_f32_e32 v105, v98, v10
	v_fmac_f32_e32 v105, v92, v12
	v_fmac_f32_e32 v105, v93, v13
	v_add_f32_e32 v75, v75, v105
	v_mul_f32_e32 v105, v21, v15
	v_fmac_f32_e32 v105, v20, v14
	v_fmac_f32_e32 v105, v18, v16
	v_fmac_f32_e32 v105, v19, v17
	v_add_f32_e32 v75, v75, v105
	v_mul_f32_e32 v105, v35, v3
	v_mul_f32_e32 v3, v43, v3
	v_fmac_f32_e32 v3, v42, v2
	v_fmac_f32_e32 v3, v38, v4
	v_fmac_f32_e32 v105, v34, v2
	v_mul_f32_e32 v106, v41, v7
	v_fmac_f32_e32 v3, v39, v5
	v_fmac_f32_e32 v105, v28, v4
	v_fmac_f32_e32 v106, v40, v6
	v_add_f32_e32 v2, 0, v3
	v_mul_f32_e32 v3, v49, v7
	v_fmac_f32_e32 v105, v29, v5
	v_fmac_f32_e32 v106, v30, v8
	v_fmac_f32_e32 v3, v48, v6
	v_add_f32_e32 v105, 0, v105
	v_fmac_f32_e32 v106, v31, v9
	v_fmac_f32_e32 v3, v44, v8
	v_add_f32_e32 v105, v105, v106
	v_mul_f32_e32 v106, v37, v11
	v_fmac_f32_e32 v3, v45, v9
	v_fmac_f32_e32 v106, v36, v10
	v_add_f32_e32 v2, v2, v3
	v_mul_f32_e32 v3, v57, v11
	v_fmac_f32_e32 v106, v32, v12
	v_fmac_f32_e32 v3, v56, v10
	v_fmac_f32_e32 v106, v33, v13
	v_fmac_f32_e32 v3, v50, v12
	v_add_f32_e32 v105, v105, v106
	v_mul_f32_e32 v106, v25, v15
	v_fmac_f32_e32 v3, v51, v13
	v_mul_f32_e32 v7, v53, v15
	v_fmac_f32_e32 v106, v24, v14
	v_add_f32_e32 v6, v2, v3
	v_fmac_f32_e32 v7, v52, v14
	ds_read_b128 v[2:5], v117 offset:16384
	v_fmac_f32_e32 v106, v22, v16
	v_fmac_f32_e32 v7, v46, v16
	v_fmac_f32_e32 v106, v23, v17
	v_fmac_f32_e32 v7, v47, v17
	v_add_f32_e32 v107, v105, v106
	v_add_f32_e32 v105, v6, v7
	ds_read_b128 v[6:9], v117 offset:17408
	ds_read_b128 v[10:13], v117 offset:18432
	ds_read_b128 v[14:17], v117 offset:19456
	s_waitcnt lgkmcnt(3)
	v_mul_f32_e32 v106, v91, v3
	v_fmac_f32_e32 v106, v90, v2
	s_waitcnt lgkmcnt(2)
	v_mul_f32_e32 v108, v89, v7
	v_fmac_f32_e32 v106, v82, v4
	v_fmac_f32_e32 v108, v88, v6
	v_fmac_f32_e32 v106, v83, v5
	v_fmac_f32_e32 v108, v80, v8
	v_add_f32_e32 v106, 0, v106
	v_fmac_f32_e32 v108, v81, v9
	v_add_f32_e32 v106, v106, v108
	s_waitcnt lgkmcnt(1)
	v_mul_f32_e32 v108, v87, v11
	v_fmac_f32_e32 v108, v86, v10
	v_fmac_f32_e32 v108, v78, v12
	v_fmac_f32_e32 v108, v79, v13
	v_add_f32_e32 v106, v106, v108
	s_waitcnt lgkmcnt(0)
	v_mul_f32_e32 v108, v85, v15
	v_fmac_f32_e32 v108, v84, v14
	v_fmac_f32_e32 v108, v76, v16
	v_fmac_f32_e32 v108, v77, v17
	v_add_f32_e32 v108, v106, v108
	v_mul_f32_e32 v106, v103, v3
	v_fmac_f32_e32 v106, v102, v2
	v_mul_f32_e32 v109, v101, v7
	v_fmac_f32_e32 v106, v96, v4
	v_fmac_f32_e32 v109, v100, v6
	v_fmac_f32_e32 v106, v97, v5
	v_fmac_f32_e32 v109, v94, v8
	v_add_f32_e32 v106, 0, v106
	v_fmac_f32_e32 v109, v95, v9
	v_add_f32_e32 v106, v106, v109
	v_mul_f32_e32 v109, v99, v11
	v_fmac_f32_e32 v109, v98, v10
	v_fmac_f32_e32 v109, v92, v12
	v_fmac_f32_e32 v109, v93, v13
	v_add_f32_e32 v106, v106, v109
	v_mul_f32_e32 v109, v21, v15
	v_fmac_f32_e32 v109, v20, v14
	v_fmac_f32_e32 v109, v18, v16
	v_fmac_f32_e32 v109, v19, v17
	v_add_f32_e32 v106, v106, v109
	v_mul_f32_e32 v109, v35, v3
	v_mul_f32_e32 v3, v43, v3
	v_fmac_f32_e32 v3, v42, v2
	v_fmac_f32_e32 v3, v38, v4
	v_fmac_f32_e32 v109, v34, v2
	v_mul_f32_e32 v110, v41, v7
	v_fmac_f32_e32 v3, v39, v5
	v_fmac_f32_e32 v109, v28, v4
	v_fmac_f32_e32 v110, v40, v6
	v_add_f32_e32 v2, 0, v3
	v_mul_f32_e32 v3, v49, v7
	v_fmac_f32_e32 v109, v29, v5
	v_fmac_f32_e32 v110, v30, v8
	v_fmac_f32_e32 v3, v48, v6
	v_add_f32_e32 v109, 0, v109
	v_fmac_f32_e32 v110, v31, v9
	v_fmac_f32_e32 v3, v44, v8
	v_add_f32_e32 v109, v109, v110
	v_mul_f32_e32 v110, v37, v11
	v_fmac_f32_e32 v3, v45, v9
	v_fmac_f32_e32 v110, v36, v10
	v_add_f32_e32 v2, v2, v3
	v_mul_f32_e32 v3, v57, v11
	v_fmac_f32_e32 v110, v32, v12
	v_fmac_f32_e32 v3, v56, v10
	v_fmac_f32_e32 v110, v33, v13
	v_fmac_f32_e32 v3, v50, v12
	v_add_f32_e32 v109, v109, v110
	v_mul_f32_e32 v110, v25, v15
	v_fmac_f32_e32 v3, v51, v13
	v_mul_f32_e32 v7, v53, v15
	v_fmac_f32_e32 v110, v24, v14
	v_add_f32_e32 v6, v2, v3
	v_fmac_f32_e32 v7, v52, v14
	ds_read_b128 v[2:5], v117 offset:20480
	v_fmac_f32_e32 v110, v22, v16
	v_fmac_f32_e32 v7, v46, v16
	v_fmac_f32_e32 v110, v23, v17
	v_fmac_f32_e32 v7, v47, v17
	v_add_f32_e32 v111, v109, v110
	v_add_f32_e32 v109, v6, v7
	ds_read_b128 v[6:9], v117 offset:21504
	ds_read_b128 v[10:13], v117 offset:22528
	ds_read_b128 v[14:17], v117 offset:23552
	s_waitcnt lgkmcnt(3)
	v_mul_f32_e32 v110, v91, v3
	v_fmac_f32_e32 v110, v90, v2
	s_waitcnt lgkmcnt(2)
	v_mul_f32_e32 v118, v89, v7
	v_fmac_f32_e32 v110, v82, v4
	v_fmac_f32_e32 v118, v88, v6
	v_fmac_f32_e32 v110, v83, v5
	v_fmac_f32_e32 v118, v80, v8
	v_add_f32_e32 v110, 0, v110
	v_fmac_f32_e32 v118, v81, v9
	v_add_f32_e32 v110, v110, v118
	s_waitcnt lgkmcnt(1)
	v_mul_f32_e32 v118, v87, v11
	v_fmac_f32_e32 v118, v86, v10
	v_fmac_f32_e32 v118, v78, v12
	v_fmac_f32_e32 v118, v79, v13
	v_add_f32_e32 v110, v110, v118
	s_waitcnt lgkmcnt(0)
	v_mul_f32_e32 v118, v85, v15
	v_fmac_f32_e32 v118, v84, v14
	v_fmac_f32_e32 v118, v76, v16
	v_fmac_f32_e32 v118, v77, v17
	v_add_f32_e32 v118, v110, v118
	v_mul_f32_e32 v110, v103, v3
	v_fmac_f32_e32 v110, v102, v2
	v_mul_f32_e32 v119, v101, v7
	v_fmac_f32_e32 v110, v96, v4
	v_fmac_f32_e32 v119, v100, v6
	v_fmac_f32_e32 v110, v97, v5
	v_fmac_f32_e32 v119, v94, v8
	v_add_f32_e32 v110, 0, v110
	v_fmac_f32_e32 v119, v95, v9
	v_add_f32_e32 v110, v110, v119
	v_mul_f32_e32 v119, v99, v11
	v_fmac_f32_e32 v119, v98, v10
	v_fmac_f32_e32 v119, v92, v12
	v_fmac_f32_e32 v119, v93, v13
	v_add_f32_e32 v110, v110, v119
	v_mul_f32_e32 v119, v21, v15
	v_fmac_f32_e32 v119, v20, v14
	v_fmac_f32_e32 v119, v18, v16
	v_fmac_f32_e32 v119, v19, v17
	v_add_f32_e32 v110, v110, v119
	v_mul_f32_e32 v119, v35, v3
	v_mul_f32_e32 v3, v43, v3
	v_fmac_f32_e32 v3, v42, v2
	v_fmac_f32_e32 v3, v38, v4
	v_fmac_f32_e32 v119, v34, v2
	v_mul_f32_e32 v120, v41, v7
	v_fmac_f32_e32 v3, v39, v5
	v_fmac_f32_e32 v119, v28, v4
	v_fmac_f32_e32 v120, v40, v6
	v_add_f32_e32 v2, 0, v3
	v_mul_f32_e32 v3, v49, v7
	v_fmac_f32_e32 v119, v29, v5
	v_fmac_f32_e32 v120, v30, v8
	v_fmac_f32_e32 v3, v48, v6
	v_add_f32_e32 v119, 0, v119
	v_fmac_f32_e32 v120, v31, v9
	v_fmac_f32_e32 v3, v44, v8
	v_add_f32_e32 v119, v119, v120
	v_mul_f32_e32 v120, v37, v11
	v_fmac_f32_e32 v3, v45, v9
	v_fmac_f32_e32 v120, v36, v10
	v_add_f32_e32 v2, v2, v3
	v_mul_f32_e32 v3, v57, v11
	v_fmac_f32_e32 v120, v32, v12
	v_fmac_f32_e32 v3, v56, v10
	v_fmac_f32_e32 v120, v33, v13
	v_fmac_f32_e32 v3, v50, v12
	v_add_f32_e32 v119, v119, v120
	v_mul_f32_e32 v120, v25, v15
	v_fmac_f32_e32 v3, v51, v13
	v_mul_f32_e32 v7, v53, v15
	v_fmac_f32_e32 v120, v24, v14
	v_add_f32_e32 v6, v2, v3
	v_fmac_f32_e32 v7, v52, v14
	ds_read_b128 v[2:5], v117 offset:24576
	v_fmac_f32_e32 v120, v22, v16
	v_fmac_f32_e32 v7, v46, v16
	v_fmac_f32_e32 v120, v23, v17
	v_fmac_f32_e32 v7, v47, v17
	v_add_f32_e32 v120, v119, v120
	v_add_f32_e32 v119, v6, v7
	ds_read_b128 v[6:9], v117 offset:25600
	ds_read_b128 v[10:13], v117 offset:26624
	ds_read_b128 v[14:17], v117 offset:27648
	s_waitcnt lgkmcnt(3)
	v_mul_f32_e32 v121, v91, v3
	v_fmac_f32_e32 v121, v90, v2
	s_waitcnt lgkmcnt(2)
	v_mul_f32_e32 v122, v89, v7
	v_fmac_f32_e32 v121, v82, v4
	v_fmac_f32_e32 v122, v88, v6
	v_fmac_f32_e32 v121, v83, v5
	v_fmac_f32_e32 v122, v80, v8
	v_add_f32_e32 v121, 0, v121
	v_fmac_f32_e32 v122, v81, v9
	v_add_f32_e32 v121, v121, v122
	s_waitcnt lgkmcnt(1)
	v_mul_f32_e32 v122, v87, v11
	v_fmac_f32_e32 v122, v86, v10
	v_fmac_f32_e32 v122, v78, v12
	v_fmac_f32_e32 v122, v79, v13
	v_add_f32_e32 v121, v121, v122
	s_waitcnt lgkmcnt(0)
	v_mul_f32_e32 v122, v85, v15
	v_fmac_f32_e32 v122, v84, v14
	v_fmac_f32_e32 v122, v76, v16
	v_fmac_f32_e32 v122, v77, v17
	v_add_f32_e32 v122, v121, v122
	v_mul_f32_e32 v121, v103, v3
	v_fmac_f32_e32 v121, v102, v2
	v_mul_f32_e32 v123, v101, v7
	v_fmac_f32_e32 v121, v96, v4
	v_fmac_f32_e32 v123, v100, v6
	v_fmac_f32_e32 v121, v97, v5
	v_fmac_f32_e32 v123, v94, v8
	v_add_f32_e32 v121, 0, v121
	v_fmac_f32_e32 v123, v95, v9
	v_add_f32_e32 v121, v121, v123
	v_mul_f32_e32 v123, v99, v11
	v_fmac_f32_e32 v123, v98, v10
	v_fmac_f32_e32 v123, v92, v12
	v_fmac_f32_e32 v123, v93, v13
	v_add_f32_e32 v121, v121, v123
	v_mul_f32_e32 v123, v21, v15
	v_fmac_f32_e32 v123, v20, v14
	v_fmac_f32_e32 v123, v18, v16
	v_fmac_f32_e32 v123, v19, v17
	v_add_f32_e32 v121, v121, v123
	v_mul_f32_e32 v123, v35, v3
	v_mul_f32_e32 v3, v43, v3
	v_fmac_f32_e32 v3, v42, v2
	v_fmac_f32_e32 v3, v38, v4
	v_fmac_f32_e32 v123, v34, v2
	v_mul_f32_e32 v124, v41, v7
	v_fmac_f32_e32 v3, v39, v5
	v_fmac_f32_e32 v123, v28, v4
	v_fmac_f32_e32 v124, v40, v6
	v_add_f32_e32 v2, 0, v3
	v_mul_f32_e32 v3, v49, v7
	v_fmac_f32_e32 v123, v29, v5
	v_fmac_f32_e32 v124, v30, v8
	v_fmac_f32_e32 v3, v48, v6
	v_add_f32_e32 v123, 0, v123
	v_fmac_f32_e32 v124, v31, v9
	v_fmac_f32_e32 v3, v44, v8
	v_add_f32_e32 v123, v123, v124
	v_mul_f32_e32 v124, v37, v11
	v_fmac_f32_e32 v3, v45, v9
	v_fmac_f32_e32 v124, v36, v10
	v_add_f32_e32 v2, v2, v3
	v_mul_f32_e32 v3, v57, v11
	v_fmac_f32_e32 v124, v32, v12
	v_fmac_f32_e32 v3, v56, v10
	v_fmac_f32_e32 v124, v33, v13
	v_fmac_f32_e32 v3, v50, v12
	v_add_f32_e32 v123, v123, v124
	v_mul_f32_e32 v124, v25, v15
	v_fmac_f32_e32 v3, v51, v13
	v_mul_f32_e32 v7, v53, v15
	v_fmac_f32_e32 v124, v24, v14
	v_add_f32_e32 v6, v2, v3
	v_fmac_f32_e32 v7, v52, v14
	ds_read_b128 v[2:5], v117 offset:28672
	v_fmac_f32_e32 v124, v22, v16
	v_fmac_f32_e32 v7, v46, v16
	v_fmac_f32_e32 v124, v23, v17
	v_fmac_f32_e32 v7, v47, v17
	v_add_f32_e32 v125, v123, v124
	v_add_f32_e32 v123, v6, v7
	ds_read_b128 v[6:9], v117 offset:29696
	ds_read_b128 v[10:13], v117 offset:30720
	ds_read_b128 v[14:17], v117 offset:31744
	s_waitcnt lgkmcnt(3)
	v_mul_f32_e32 v124, v91, v3
	v_fmac_f32_e32 v124, v90, v2
	s_waitcnt lgkmcnt(2)
	v_mul_f32_e32 v126, v89, v7
	v_fmac_f32_e32 v124, v82, v4
	v_fmac_f32_e32 v126, v88, v6
	v_fmac_f32_e32 v124, v83, v5
	v_fmac_f32_e32 v126, v80, v8
	v_add_f32_e32 v124, 0, v124
	v_fmac_f32_e32 v126, v81, v9
	v_add_f32_e32 v124, v124, v126
	s_waitcnt lgkmcnt(1)
	v_mul_f32_e32 v126, v87, v11
	v_fmac_f32_e32 v126, v86, v10
	v_fmac_f32_e32 v126, v78, v12
	v_fmac_f32_e32 v126, v79, v13
	v_add_f32_e32 v124, v124, v126
	s_waitcnt lgkmcnt(0)
	v_mul_f32_e32 v126, v85, v15
	v_fmac_f32_e32 v126, v84, v14
	v_fmac_f32_e32 v126, v76, v16
	v_fmac_f32_e32 v126, v77, v17
	v_add_f32_e32 v126, v124, v126
	v_mul_f32_e32 v124, v103, v3
	v_fmac_f32_e32 v124, v102, v2
	v_mul_f32_e32 v127, v101, v7
	v_fmac_f32_e32 v124, v96, v4
	v_fmac_f32_e32 v127, v100, v6
	v_fmac_f32_e32 v124, v97, v5
	v_fmac_f32_e32 v127, v94, v8
	v_add_f32_e32 v124, 0, v124
	v_fmac_f32_e32 v127, v95, v9
	v_add_f32_e32 v124, v124, v127
	v_mul_f32_e32 v127, v99, v11
	v_fmac_f32_e32 v127, v98, v10
	v_fmac_f32_e32 v127, v92, v12
	v_fmac_f32_e32 v127, v93, v13
	v_add_f32_e32 v124, v124, v127
	v_mul_f32_e32 v127, v21, v15
	v_fmac_f32_e32 v127, v20, v14
	v_fmac_f32_e32 v127, v18, v16
	v_fmac_f32_e32 v127, v19, v17
	v_add_f32_e32 v124, v124, v127
	v_mul_f32_e32 v127, v35, v3
	v_mul_f32_e32 v3, v43, v3
	v_fmac_f32_e32 v3, v42, v2
	v_fmac_f32_e32 v3, v38, v4
	v_fmac_f32_e32 v127, v34, v2
	v_mul_f32_e32 v128, v41, v7
	v_fmac_f32_e32 v3, v39, v5
	v_fmac_f32_e32 v127, v28, v4
	v_fmac_f32_e32 v128, v40, v6
	v_add_f32_e32 v2, 0, v3
	v_mul_f32_e32 v3, v49, v7
	v_fmac_f32_e32 v127, v29, v5
	v_fmac_f32_e32 v128, v30, v8
	v_fmac_f32_e32 v3, v48, v6
	v_add_f32_e32 v127, 0, v127
	v_fmac_f32_e32 v128, v31, v9
	v_fmac_f32_e32 v3, v44, v8
	v_add_f32_e32 v127, v127, v128
	v_mul_f32_e32 v128, v37, v11
	v_fmac_f32_e32 v3, v45, v9
	v_fmac_f32_e32 v128, v36, v10
	v_add_f32_e32 v2, v2, v3
	v_mul_f32_e32 v3, v57, v11
	v_fmac_f32_e32 v128, v32, v12
	v_fmac_f32_e32 v3, v56, v10
	v_fmac_f32_e32 v128, v33, v13
	v_fmac_f32_e32 v3, v50, v12
	v_add_f32_e32 v127, v127, v128
	v_mul_f32_e32 v128, v25, v15
	v_fmac_f32_e32 v3, v51, v13
	v_mul_f32_e32 v7, v53, v15
	v_fmac_f32_e32 v128, v24, v14
	v_add_f32_e32 v6, v2, v3
	v_fmac_f32_e32 v7, v52, v14
	ds_read_b128 v[2:5], v117 offset:32768
	v_fmac_f32_e32 v128, v22, v16
	v_fmac_f32_e32 v7, v46, v16
	v_fmac_f32_e32 v128, v23, v17
	v_fmac_f32_e32 v7, v47, v17
	v_add_f32_e32 v129, v127, v128
	v_add_f32_e32 v127, v6, v7
	ds_read_b128 v[6:9], v117 offset:33792
	ds_read_b128 v[10:13], v117 offset:34816
	ds_read_b128 v[14:17], v117 offset:35840
	s_waitcnt lgkmcnt(3)
	v_mul_f32_e32 v128, v91, v3
	v_fmac_f32_e32 v128, v90, v2
	s_waitcnt lgkmcnt(2)
	v_mul_f32_e32 v130, v89, v7
	v_fmac_f32_e32 v128, v82, v4
	v_fmac_f32_e32 v130, v88, v6
	v_fmac_f32_e32 v128, v83, v5
	v_fmac_f32_e32 v130, v80, v8
	v_add_f32_e32 v128, 0, v128
	v_fmac_f32_e32 v130, v81, v9
	v_add_f32_e32 v128, v128, v130
	s_waitcnt lgkmcnt(1)
	v_mul_f32_e32 v130, v87, v11
	v_fmac_f32_e32 v130, v86, v10
	v_fmac_f32_e32 v130, v78, v12
	v_fmac_f32_e32 v130, v79, v13
	v_add_f32_e32 v128, v128, v130
	s_waitcnt lgkmcnt(0)
	v_mul_f32_e32 v130, v85, v15
	v_fmac_f32_e32 v130, v84, v14
	v_fmac_f32_e32 v130, v76, v16
	v_fmac_f32_e32 v130, v77, v17
	v_add_f32_e32 v130, v128, v130
	v_mul_f32_e32 v128, v103, v3
	v_fmac_f32_e32 v128, v102, v2
	v_mul_f32_e32 v131, v101, v7
	v_fmac_f32_e32 v128, v96, v4
	v_fmac_f32_e32 v131, v100, v6
	v_fmac_f32_e32 v128, v97, v5
	v_fmac_f32_e32 v131, v94, v8
	v_add_f32_e32 v128, 0, v128
	v_fmac_f32_e32 v131, v95, v9
	v_add_f32_e32 v128, v128, v131
	v_mul_f32_e32 v131, v99, v11
	v_fmac_f32_e32 v131, v98, v10
	v_fmac_f32_e32 v131, v92, v12
	v_fmac_f32_e32 v131, v93, v13
	v_add_f32_e32 v128, v128, v131
	v_mul_f32_e32 v131, v21, v15
	v_fmac_f32_e32 v131, v20, v14
	v_fmac_f32_e32 v131, v18, v16
	v_fmac_f32_e32 v131, v19, v17
	v_add_f32_e32 v128, v128, v131
	v_mul_f32_e32 v131, v35, v3
	v_mul_f32_e32 v3, v43, v3
	v_fmac_f32_e32 v3, v42, v2
	v_fmac_f32_e32 v3, v38, v4
	v_fmac_f32_e32 v131, v34, v2
	v_mul_f32_e32 v132, v41, v7
	v_fmac_f32_e32 v3, v39, v5
	v_fmac_f32_e32 v131, v28, v4
	v_fmac_f32_e32 v132, v40, v6
	v_add_f32_e32 v2, 0, v3
	v_mul_f32_e32 v3, v49, v7
	v_fmac_f32_e32 v131, v29, v5
	v_fmac_f32_e32 v132, v30, v8
	v_fmac_f32_e32 v3, v48, v6
	v_add_f32_e32 v131, 0, v131
	v_fmac_f32_e32 v132, v31, v9
	v_fmac_f32_e32 v3, v44, v8
	v_add_f32_e32 v131, v131, v132
	v_mul_f32_e32 v132, v37, v11
	v_fmac_f32_e32 v3, v45, v9
	v_fmac_f32_e32 v132, v36, v10
	v_add_f32_e32 v2, v2, v3
	v_mul_f32_e32 v3, v57, v11
	v_fmac_f32_e32 v132, v32, v12
	v_fmac_f32_e32 v3, v56, v10
	v_fmac_f32_e32 v132, v33, v13
	v_fmac_f32_e32 v3, v50, v12
	v_add_f32_e32 v131, v131, v132
	v_mul_f32_e32 v132, v25, v15
	v_fmac_f32_e32 v3, v51, v13
	v_mul_f32_e32 v7, v53, v15
	v_fmac_f32_e32 v132, v24, v14
	v_add_f32_e32 v6, v2, v3
	v_fmac_f32_e32 v7, v52, v14
	ds_read_b128 v[2:5], v117 offset:36864
	v_fmac_f32_e32 v132, v22, v16
	v_fmac_f32_e32 v7, v46, v16
	v_fmac_f32_e32 v132, v23, v17
	v_fmac_f32_e32 v7, v47, v17
	v_add_f32_e32 v132, v131, v132
	v_add_f32_e32 v131, v6, v7
	ds_read_b128 v[6:9], v117 offset:37888
	ds_read_b128 v[10:13], v117 offset:38912
	ds_read_b128 v[14:17], v117 offset:39936
	s_waitcnt lgkmcnt(3)
	v_mul_f32_e32 v133, v91, v3
	v_fmac_f32_e32 v133, v90, v2
	s_waitcnt lgkmcnt(2)
	v_mul_f32_e32 v134, v89, v7
	v_fmac_f32_e32 v133, v82, v4
	v_fmac_f32_e32 v134, v88, v6
	v_fmac_f32_e32 v133, v83, v5
	v_fmac_f32_e32 v134, v80, v8
	v_add_f32_e32 v133, 0, v133
	v_fmac_f32_e32 v134, v81, v9
	v_add_f32_e32 v133, v133, v134
	s_waitcnt lgkmcnt(1)
	v_mul_f32_e32 v134, v87, v11
	v_fmac_f32_e32 v134, v86, v10
	v_fmac_f32_e32 v134, v78, v12
	v_fmac_f32_e32 v134, v79, v13
	v_add_f32_e32 v133, v133, v134
	s_waitcnt lgkmcnt(0)
	v_mul_f32_e32 v134, v85, v15
	v_fmac_f32_e32 v134, v84, v14
	v_fmac_f32_e32 v134, v76, v16
	v_fmac_f32_e32 v134, v77, v17
	v_add_f32_e32 v134, v133, v134
	v_mul_f32_e32 v133, v103, v3
	v_fmac_f32_e32 v133, v102, v2
	v_mul_f32_e32 v135, v101, v7
	v_fmac_f32_e32 v133, v96, v4
	v_fmac_f32_e32 v135, v100, v6
	v_fmac_f32_e32 v133, v97, v5
	v_fmac_f32_e32 v135, v94, v8
	v_add_f32_e32 v133, 0, v133
	v_fmac_f32_e32 v135, v95, v9
	v_add_f32_e32 v133, v133, v135
	v_mul_f32_e32 v135, v99, v11
	v_fmac_f32_e32 v135, v98, v10
	v_fmac_f32_e32 v135, v92, v12
	v_fmac_f32_e32 v135, v93, v13
	v_add_f32_e32 v133, v133, v135
	v_mul_f32_e32 v135, v21, v15
	v_fmac_f32_e32 v135, v20, v14
	v_fmac_f32_e32 v135, v18, v16
	v_fmac_f32_e32 v135, v19, v17
	v_add_f32_e32 v133, v133, v135
	v_mul_f32_e32 v135, v35, v3
	v_mul_f32_e32 v3, v43, v3
	v_fmac_f32_e32 v3, v42, v2
	v_fmac_f32_e32 v3, v38, v4
	v_fmac_f32_e32 v135, v34, v2
	v_mul_f32_e32 v136, v41, v7
	v_fmac_f32_e32 v3, v39, v5
	v_fmac_f32_e32 v135, v28, v4
	v_fmac_f32_e32 v136, v40, v6
	v_add_f32_e32 v2, 0, v3
	v_mul_f32_e32 v3, v49, v7
	v_fmac_f32_e32 v135, v29, v5
	v_fmac_f32_e32 v136, v30, v8
	v_fmac_f32_e32 v3, v48, v6
	v_add_f32_e32 v135, 0, v135
	v_fmac_f32_e32 v136, v31, v9
	v_fmac_f32_e32 v3, v44, v8
	v_add_f32_e32 v135, v135, v136
	v_mul_f32_e32 v136, v37, v11
	v_fmac_f32_e32 v3, v45, v9
	v_fmac_f32_e32 v136, v36, v10
	v_add_f32_e32 v2, v2, v3
	v_mul_f32_e32 v3, v57, v11
	v_fmac_f32_e32 v136, v32, v12
	v_fmac_f32_e32 v3, v56, v10
	v_fmac_f32_e32 v136, v33, v13
	v_fmac_f32_e32 v3, v50, v12
	v_add_f32_e32 v135, v135, v136
	v_mul_f32_e32 v136, v25, v15
	v_fmac_f32_e32 v3, v51, v13
	v_mul_f32_e32 v7, v53, v15
	v_fmac_f32_e32 v136, v24, v14
	v_add_f32_e32 v6, v2, v3
	v_fmac_f32_e32 v7, v52, v14
	ds_read_b128 v[2:5], v117 offset:40960
	v_fmac_f32_e32 v136, v22, v16
	v_fmac_f32_e32 v7, v46, v16
	v_fmac_f32_e32 v136, v23, v17
	v_fmac_f32_e32 v7, v47, v17
	v_add_f32_e32 v137, v135, v136
	v_add_f32_e32 v135, v6, v7
	ds_read_b128 v[6:9], v117 offset:41984
	ds_read_b128 v[10:13], v117 offset:43008
	ds_read_b128 v[14:17], v117 offset:44032
	s_waitcnt lgkmcnt(3)
	v_mul_f32_e32 v136, v91, v3
	v_fmac_f32_e32 v136, v90, v2
	s_waitcnt lgkmcnt(2)
	v_mul_f32_e32 v138, v89, v7
	v_fmac_f32_e32 v136, v82, v4
	v_fmac_f32_e32 v138, v88, v6
	v_fmac_f32_e32 v136, v83, v5
	v_fmac_f32_e32 v138, v80, v8
	v_add_f32_e32 v136, 0, v136
	v_fmac_f32_e32 v138, v81, v9
	v_add_f32_e32 v136, v136, v138
	s_waitcnt lgkmcnt(1)
	v_mul_f32_e32 v138, v87, v11
	v_fmac_f32_e32 v138, v86, v10
	v_fmac_f32_e32 v138, v78, v12
	v_fmac_f32_e32 v138, v79, v13
	v_add_f32_e32 v136, v136, v138
	s_waitcnt lgkmcnt(0)
	v_mul_f32_e32 v138, v85, v15
	v_fmac_f32_e32 v138, v84, v14
	v_fmac_f32_e32 v138, v76, v16
	v_fmac_f32_e32 v138, v77, v17
	v_add_f32_e32 v138, v136, v138
	v_mul_f32_e32 v136, v103, v3
	v_fmac_f32_e32 v136, v102, v2
	v_mul_f32_e32 v139, v101, v7
	v_fmac_f32_e32 v136, v96, v4
	v_fmac_f32_e32 v139, v100, v6
	v_fmac_f32_e32 v136, v97, v5
	v_fmac_f32_e32 v139, v94, v8
	v_add_f32_e32 v136, 0, v136
	v_fmac_f32_e32 v139, v95, v9
	v_add_f32_e32 v136, v136, v139
	v_mul_f32_e32 v139, v99, v11
	v_fmac_f32_e32 v139, v98, v10
	v_fmac_f32_e32 v139, v92, v12
	v_fmac_f32_e32 v139, v93, v13
	v_add_f32_e32 v136, v136, v139
	v_mul_f32_e32 v139, v21, v15
	v_fmac_f32_e32 v139, v20, v14
	v_fmac_f32_e32 v139, v18, v16
	v_fmac_f32_e32 v139, v19, v17
	v_add_f32_e32 v136, v136, v139
	v_mul_f32_e32 v139, v35, v3
	v_mul_f32_e32 v3, v43, v3
	v_fmac_f32_e32 v3, v42, v2
	v_fmac_f32_e32 v3, v38, v4
	v_fmac_f32_e32 v139, v34, v2
	v_mul_f32_e32 v140, v41, v7
	v_fmac_f32_e32 v3, v39, v5
	v_fmac_f32_e32 v139, v28, v4
	v_fmac_f32_e32 v140, v40, v6
	v_add_f32_e32 v2, 0, v3
	v_mul_f32_e32 v3, v49, v7
	v_fmac_f32_e32 v139, v29, v5
	v_fmac_f32_e32 v140, v30, v8
	v_fmac_f32_e32 v3, v48, v6
	v_add_f32_e32 v139, 0, v139
	v_fmac_f32_e32 v140, v31, v9
	v_fmac_f32_e32 v3, v44, v8
	v_add_f32_e32 v139, v139, v140
	v_mul_f32_e32 v140, v37, v11
	v_fmac_f32_e32 v3, v45, v9
	v_fmac_f32_e32 v140, v36, v10
	v_add_f32_e32 v2, v2, v3
	v_mul_f32_e32 v3, v57, v11
	v_fmac_f32_e32 v140, v32, v12
	v_fmac_f32_e32 v3, v56, v10
	v_fmac_f32_e32 v140, v33, v13
	v_fmac_f32_e32 v3, v50, v12
	v_add_f32_e32 v139, v139, v140
	v_mul_f32_e32 v140, v25, v15
	v_fmac_f32_e32 v3, v51, v13
	v_mul_f32_e32 v7, v53, v15
	v_fmac_f32_e32 v140, v24, v14
	v_add_f32_e32 v6, v2, v3
	v_fmac_f32_e32 v7, v52, v14
	ds_read_b128 v[2:5], v117 offset:45056
	v_fmac_f32_e32 v140, v22, v16
	v_fmac_f32_e32 v7, v46, v16
	v_fmac_f32_e32 v140, v23, v17
	v_fmac_f32_e32 v7, v47, v17
	v_add_f32_e32 v141, v139, v140
	v_add_f32_e32 v139, v6, v7
	ds_read_b128 v[6:9], v117 offset:46080
	ds_read_b128 v[10:13], v117 offset:47104
	ds_read_b128 v[14:17], v117 offset:48128
	s_waitcnt lgkmcnt(3)
	v_mul_f32_e32 v140, v91, v3
	v_fmac_f32_e32 v140, v90, v2
	s_waitcnt lgkmcnt(2)
	v_mul_f32_e32 v142, v89, v7
	v_fmac_f32_e32 v140, v82, v4
	v_fmac_f32_e32 v142, v88, v6
	v_fmac_f32_e32 v140, v83, v5
	v_fmac_f32_e32 v142, v80, v8
	v_add_f32_e32 v140, 0, v140
	v_fmac_f32_e32 v142, v81, v9
	v_add_f32_e32 v140, v140, v142
	s_waitcnt lgkmcnt(1)
	v_mul_f32_e32 v142, v87, v11
	v_fmac_f32_e32 v142, v86, v10
	v_fmac_f32_e32 v142, v78, v12
	v_fmac_f32_e32 v142, v79, v13
	v_add_f32_e32 v140, v140, v142
	s_waitcnt lgkmcnt(0)
	v_mul_f32_e32 v142, v85, v15
	v_fmac_f32_e32 v142, v84, v14
	v_fmac_f32_e32 v142, v76, v16
	v_fmac_f32_e32 v142, v77, v17
	v_add_f32_e32 v142, v140, v142
	v_mul_f32_e32 v140, v103, v3
	v_fmac_f32_e32 v140, v102, v2
	v_mul_f32_e32 v143, v101, v7
	v_fmac_f32_e32 v140, v96, v4
	v_fmac_f32_e32 v143, v100, v6
	v_fmac_f32_e32 v140, v97, v5
	v_fmac_f32_e32 v143, v94, v8
	v_add_f32_e32 v140, 0, v140
	v_fmac_f32_e32 v143, v95, v9
	v_add_f32_e32 v140, v140, v143
	v_mul_f32_e32 v143, v99, v11
	v_fmac_f32_e32 v143, v98, v10
	v_fmac_f32_e32 v143, v92, v12
	v_fmac_f32_e32 v143, v93, v13
	v_add_f32_e32 v140, v140, v143
	v_mul_f32_e32 v143, v21, v15
	v_fmac_f32_e32 v143, v20, v14
	v_fmac_f32_e32 v143, v18, v16
	v_fmac_f32_e32 v143, v19, v17
	v_add_f32_e32 v140, v140, v143
	v_mul_f32_e32 v143, v35, v3
	v_mul_f32_e32 v3, v43, v3
	v_fmac_f32_e32 v3, v42, v2
	v_fmac_f32_e32 v3, v38, v4
	v_fmac_f32_e32 v143, v34, v2
	v_mul_f32_e32 v144, v41, v7
	v_fmac_f32_e32 v3, v39, v5
	v_fmac_f32_e32 v143, v28, v4
	v_fmac_f32_e32 v144, v40, v6
	v_add_f32_e32 v2, 0, v3
	v_mul_f32_e32 v3, v49, v7
	v_fmac_f32_e32 v143, v29, v5
	v_fmac_f32_e32 v144, v30, v8
	v_fmac_f32_e32 v3, v48, v6
	v_add_f32_e32 v143, 0, v143
	v_fmac_f32_e32 v144, v31, v9
	v_fmac_f32_e32 v3, v44, v8
	v_add_f32_e32 v143, v143, v144
	v_mul_f32_e32 v144, v37, v11
	v_fmac_f32_e32 v3, v45, v9
	v_fmac_f32_e32 v144, v36, v10
	v_add_f32_e32 v2, v2, v3
	v_mul_f32_e32 v3, v57, v11
	v_fmac_f32_e32 v144, v32, v12
	v_fmac_f32_e32 v3, v56, v10
	v_fmac_f32_e32 v144, v33, v13
	v_fmac_f32_e32 v3, v50, v12
	v_add_f32_e32 v143, v143, v144
	v_mul_f32_e32 v144, v25, v15
	v_fmac_f32_e32 v3, v51, v13
	v_mul_f32_e32 v7, v53, v15
	v_fmac_f32_e32 v144, v24, v14
	v_add_f32_e32 v6, v2, v3
	v_fmac_f32_e32 v7, v52, v14
	ds_read_b128 v[2:5], v117 offset:49152
	v_fmac_f32_e32 v144, v22, v16
	v_fmac_f32_e32 v7, v46, v16
	v_fmac_f32_e32 v144, v23, v17
	v_fmac_f32_e32 v7, v47, v17
	v_add_f32_e32 v144, v143, v144
	v_add_f32_e32 v143, v6, v7
	ds_read_b128 v[6:9], v117 offset:50176
	ds_read_b128 v[10:13], v117 offset:51200
	ds_read_b128 v[14:17], v117 offset:52224
	s_waitcnt lgkmcnt(3)
	v_mul_f32_e32 v145, v91, v3
	v_fmac_f32_e32 v145, v90, v2
	s_waitcnt lgkmcnt(2)
	v_mul_f32_e32 v146, v89, v7
	v_fmac_f32_e32 v145, v82, v4
	v_fmac_f32_e32 v146, v88, v6
	v_fmac_f32_e32 v145, v83, v5
	v_fmac_f32_e32 v146, v80, v8
	v_add_f32_e32 v145, 0, v145
	v_fmac_f32_e32 v146, v81, v9
	v_add_f32_e32 v145, v145, v146
	s_waitcnt lgkmcnt(1)
	v_mul_f32_e32 v146, v87, v11
	v_fmac_f32_e32 v146, v86, v10
	v_fmac_f32_e32 v146, v78, v12
	v_fmac_f32_e32 v146, v79, v13
	v_add_f32_e32 v145, v145, v146
	s_waitcnt lgkmcnt(0)
	v_mul_f32_e32 v146, v85, v15
	v_fmac_f32_e32 v146, v84, v14
	v_fmac_f32_e32 v146, v76, v16
	v_fmac_f32_e32 v146, v77, v17
	v_add_f32_e32 v146, v145, v146
	v_mul_f32_e32 v145, v103, v3
	v_fmac_f32_e32 v145, v102, v2
	v_mul_f32_e32 v147, v101, v7
	v_fmac_f32_e32 v145, v96, v4
	v_fmac_f32_e32 v147, v100, v6
	v_fmac_f32_e32 v145, v97, v5
	v_fmac_f32_e32 v147, v94, v8
	v_add_f32_e32 v145, 0, v145
	v_fmac_f32_e32 v147, v95, v9
	v_add_f32_e32 v145, v145, v147
	v_mul_f32_e32 v147, v99, v11
	v_fmac_f32_e32 v147, v98, v10
	v_fmac_f32_e32 v147, v92, v12
	v_fmac_f32_e32 v147, v93, v13
	v_add_f32_e32 v145, v145, v147
	v_mul_f32_e32 v147, v21, v15
	v_fmac_f32_e32 v147, v20, v14
	v_fmac_f32_e32 v147, v18, v16
	v_fmac_f32_e32 v147, v19, v17
	v_add_f32_e32 v145, v145, v147
	v_mul_f32_e32 v147, v35, v3
	v_mul_f32_e32 v3, v43, v3
	v_fmac_f32_e32 v3, v42, v2
	v_fmac_f32_e32 v3, v38, v4
	v_fmac_f32_e32 v147, v34, v2
	v_mul_f32_e32 v148, v41, v7
	v_fmac_f32_e32 v3, v39, v5
	v_fmac_f32_e32 v147, v28, v4
	v_fmac_f32_e32 v148, v40, v6
	v_add_f32_e32 v2, 0, v3
	v_mul_f32_e32 v3, v49, v7
	v_fmac_f32_e32 v147, v29, v5
	v_fmac_f32_e32 v148, v30, v8
	v_fmac_f32_e32 v3, v48, v6
	v_add_f32_e32 v147, 0, v147
	v_fmac_f32_e32 v148, v31, v9
	v_fmac_f32_e32 v3, v44, v8
	v_add_f32_e32 v147, v147, v148
	v_mul_f32_e32 v148, v37, v11
	v_fmac_f32_e32 v3, v45, v9
	v_fmac_f32_e32 v148, v36, v10
	v_add_f32_e32 v2, v2, v3
	v_mul_f32_e32 v3, v57, v11
	v_fmac_f32_e32 v148, v32, v12
	v_fmac_f32_e32 v3, v56, v10
	v_fmac_f32_e32 v148, v33, v13
	v_fmac_f32_e32 v3, v50, v12
	v_add_f32_e32 v147, v147, v148
	v_mul_f32_e32 v148, v25, v15
	v_fmac_f32_e32 v3, v51, v13
	v_mul_f32_e32 v7, v53, v15
	v_fmac_f32_e32 v148, v24, v14
	v_add_f32_e32 v6, v2, v3
	v_fmac_f32_e32 v7, v52, v14
	ds_read_b128 v[2:5], v117 offset:53248
	v_fmac_f32_e32 v148, v22, v16
	v_fmac_f32_e32 v7, v46, v16
	v_fmac_f32_e32 v148, v23, v17
	v_fmac_f32_e32 v7, v47, v17
	v_add_f32_e32 v149, v147, v148
	v_add_f32_e32 v147, v6, v7
	ds_read_b128 v[6:9], v117 offset:54272
	ds_read_b128 v[10:13], v117 offset:55296
	ds_read_b128 v[14:17], v117 offset:56320
	s_waitcnt lgkmcnt(3)
	v_mul_f32_e32 v148, v91, v3
	v_fmac_f32_e32 v148, v90, v2
	s_waitcnt lgkmcnt(2)
	v_mul_f32_e32 v150, v89, v7
	v_fmac_f32_e32 v148, v82, v4
	v_fmac_f32_e32 v150, v88, v6
	v_fmac_f32_e32 v148, v83, v5
	v_fmac_f32_e32 v150, v80, v8
	v_add_f32_e32 v148, 0, v148
	v_fmac_f32_e32 v150, v81, v9
	v_add_f32_e32 v148, v148, v150
	s_waitcnt lgkmcnt(1)
	v_mul_f32_e32 v150, v87, v11
	v_fmac_f32_e32 v150, v86, v10
	v_fmac_f32_e32 v150, v78, v12
	v_fmac_f32_e32 v150, v79, v13
	v_add_f32_e32 v148, v148, v150
	s_waitcnt lgkmcnt(0)
	v_mul_f32_e32 v150, v85, v15
	v_fmac_f32_e32 v150, v84, v14
	v_fmac_f32_e32 v150, v76, v16
	v_fmac_f32_e32 v150, v77, v17
	v_add_f32_e32 v150, v148, v150
	v_mul_f32_e32 v148, v103, v3
	v_fmac_f32_e32 v148, v102, v2
	v_mul_f32_e32 v151, v101, v7
	v_fmac_f32_e32 v148, v96, v4
	v_fmac_f32_e32 v151, v100, v6
	v_fmac_f32_e32 v148, v97, v5
	v_fmac_f32_e32 v151, v94, v8
	v_add_f32_e32 v148, 0, v148
	v_fmac_f32_e32 v151, v95, v9
	v_add_f32_e32 v148, v148, v151
	v_mul_f32_e32 v151, v99, v11
	v_fmac_f32_e32 v151, v98, v10
	v_fmac_f32_e32 v151, v92, v12
	v_fmac_f32_e32 v151, v93, v13
	v_add_f32_e32 v148, v148, v151
	v_mul_f32_e32 v151, v21, v15
	v_fmac_f32_e32 v151, v20, v14
	v_fmac_f32_e32 v151, v18, v16
	v_fmac_f32_e32 v151, v19, v17
	v_add_f32_e32 v148, v148, v151
	v_mul_f32_e32 v151, v35, v3
	v_mul_f32_e32 v3, v43, v3
	v_fmac_f32_e32 v3, v42, v2
	v_fmac_f32_e32 v3, v38, v4
	v_fmac_f32_e32 v151, v34, v2
	v_mul_f32_e32 v152, v41, v7
	v_fmac_f32_e32 v3, v39, v5
	v_fmac_f32_e32 v151, v28, v4
	v_fmac_f32_e32 v152, v40, v6
	v_add_f32_e32 v2, 0, v3
	v_mul_f32_e32 v3, v49, v7
	v_fmac_f32_e32 v151, v29, v5
	v_fmac_f32_e32 v152, v30, v8
	v_fmac_f32_e32 v3, v48, v6
	v_add_f32_e32 v151, 0, v151
	v_fmac_f32_e32 v152, v31, v9
	v_fmac_f32_e32 v3, v44, v8
	v_add_f32_e32 v151, v151, v152
	v_mul_f32_e32 v152, v37, v11
	v_fmac_f32_e32 v3, v45, v9
	v_fmac_f32_e32 v152, v36, v10
	v_add_f32_e32 v2, v2, v3
	v_mul_f32_e32 v3, v57, v11
	v_fmac_f32_e32 v152, v32, v12
	v_fmac_f32_e32 v3, v56, v10
	v_fmac_f32_e32 v152, v33, v13
	v_fmac_f32_e32 v3, v50, v12
	v_add_f32_e32 v151, v151, v152
	v_mul_f32_e32 v152, v25, v15
	v_fmac_f32_e32 v3, v51, v13
	v_mul_f32_e32 v7, v53, v15
	v_fmac_f32_e32 v152, v24, v14
	v_add_f32_e32 v6, v2, v3
	v_fmac_f32_e32 v7, v52, v14
	ds_read_b128 v[2:5], v117 offset:57344
	v_fmac_f32_e32 v152, v22, v16
	v_fmac_f32_e32 v7, v46, v16
	v_fmac_f32_e32 v152, v23, v17
	v_fmac_f32_e32 v7, v47, v17
	v_add_f32_e32 v153, v151, v152
	v_add_f32_e32 v151, v6, v7
	ds_read_b128 v[6:9], v117 offset:58368
	ds_read_b128 v[10:13], v117 offset:59392
	ds_read_b128 v[14:17], v117 offset:60416
	s_waitcnt lgkmcnt(3)
	v_mul_f32_e32 v152, v91, v3
	v_fmac_f32_e32 v152, v90, v2
	s_waitcnt lgkmcnt(2)
	v_mul_f32_e32 v154, v89, v7
	v_fmac_f32_e32 v152, v82, v4
	v_fmac_f32_e32 v154, v88, v6
	v_fmac_f32_e32 v152, v83, v5
	v_fmac_f32_e32 v154, v80, v8
	v_add_f32_e32 v152, 0, v152
	v_fmac_f32_e32 v154, v81, v9
	v_add_f32_e32 v152, v152, v154
	s_waitcnt lgkmcnt(1)
	v_mul_f32_e32 v154, v87, v11
	v_fmac_f32_e32 v154, v86, v10
	v_fmac_f32_e32 v154, v78, v12
	v_fmac_f32_e32 v154, v79, v13
	v_add_f32_e32 v152, v152, v154
	s_waitcnt lgkmcnt(0)
	v_mul_f32_e32 v154, v85, v15
	v_fmac_f32_e32 v154, v84, v14
	v_fmac_f32_e32 v154, v76, v16
	v_fmac_f32_e32 v154, v77, v17
	v_add_f32_e32 v154, v152, v154
	v_mul_f32_e32 v152, v103, v3
	v_fmac_f32_e32 v152, v102, v2
	v_mul_f32_e32 v155, v101, v7
	v_fmac_f32_e32 v152, v96, v4
	v_fmac_f32_e32 v155, v100, v6
	v_fmac_f32_e32 v152, v97, v5
	v_fmac_f32_e32 v155, v94, v8
	v_add_f32_e32 v152, 0, v152
	v_fmac_f32_e32 v155, v95, v9
	v_add_f32_e32 v152, v152, v155
	v_mul_f32_e32 v155, v99, v11
	v_fmac_f32_e32 v155, v98, v10
	v_fmac_f32_e32 v155, v92, v12
	v_fmac_f32_e32 v155, v93, v13
	v_add_f32_e32 v152, v152, v155
	v_mul_f32_e32 v155, v21, v15
	v_fmac_f32_e32 v155, v20, v14
	v_fmac_f32_e32 v155, v18, v16
	v_fmac_f32_e32 v155, v19, v17
	v_add_f32_e32 v152, v152, v155
	v_mul_f32_e32 v155, v35, v3
	v_mul_f32_e32 v3, v43, v3
	v_fmac_f32_e32 v3, v42, v2
	v_fmac_f32_e32 v3, v38, v4
	v_fmac_f32_e32 v3, v39, v5
	v_fmac_f32_e32 v155, v34, v2
	v_mul_f32_e32 v156, v41, v7
	v_add_f32_e32 v2, 0, v3
	v_mul_f32_e32 v3, v49, v7
	v_fmac_f32_e32 v155, v28, v4
	v_fmac_f32_e32 v156, v40, v6
	v_fmac_f32_e32 v3, v48, v6
	v_fmac_f32_e32 v155, v29, v5
	v_fmac_f32_e32 v156, v30, v8
	v_fmac_f32_e32 v3, v44, v8
	v_add_f32_e32 v155, 0, v155
	v_fmac_f32_e32 v156, v31, v9
	v_fmac_f32_e32 v3, v45, v9
	v_add_f32_e32 v155, v155, v156
	v_mul_f32_e32 v156, v37, v11
	v_add_f32_e32 v2, v2, v3
	v_mul_f32_e32 v3, v57, v11
	v_fmac_f32_e32 v156, v36, v10
	v_fmac_f32_e32 v3, v56, v10
	v_fmac_f32_e32 v156, v32, v12
	v_fmac_f32_e32 v3, v50, v12
	v_fmac_f32_e32 v156, v33, v13
	v_fmac_f32_e32 v3, v51, v13
	v_add_f32_e32 v155, v155, v156
	v_mul_f32_e32 v156, v25, v15
	v_add_f32_e32 v2, v2, v3
	v_mul_f32_e32 v3, v53, v15
	v_fmac_f32_e32 v156, v24, v14
	v_fmac_f32_e32 v3, v52, v14
	v_fmac_f32_e32 v156, v22, v16
	v_fmac_f32_e32 v3, v46, v16
	v_fmac_f32_e32 v156, v23, v17
	v_fmac_f32_e32 v3, v47, v17
	ds_read_b128 v[14:17], v117 offset:61440
	v_add_f32_e32 v156, v155, v156
	v_add_f32_e32 v155, v2, v3
	ds_read_b128 v[10:13], v117 offset:62464
	ds_read_b128 v[6:9], v117 offset:63488
	ds_read_b128 v[2:5], v117 offset:64512
	v_readlane_b32 s1, v254, 57
	s_waitcnt lgkmcnt(3)
	v_mul_f32_e32 v91, v91, v15
	v_fmac_f32_e32 v91, v90, v14
	v_fmac_f32_e32 v91, v82, v16
	v_fmac_f32_e32 v91, v83, v17
	s_waitcnt lgkmcnt(2)
	v_mul_f32_e32 v83, v89, v11
	v_fmac_f32_e32 v83, v88, v10
	s_waitcnt lgkmcnt(0)
	v_mul_f32_e32 v21, v21, v3
	v_fmac_f32_e32 v83, v80, v12
	v_fmac_f32_e32 v21, v20, v2
	v_fmac_f32_e32 v83, v81, v13
	v_mul_f32_e32 v81, v87, v7
	v_fmac_f32_e32 v21, v18, v4
	v_fmac_f32_e32 v81, v86, v6
	v_fmac_f32_e32 v21, v19, v5
	v_mul_f32_e32 v19, v35, v15
	v_fmac_f32_e32 v81, v78, v8
	v_fmac_f32_e32 v19, v34, v14
	v_mul_f32_e32 v20, v41, v11
	v_fmac_f32_e32 v81, v79, v9
	v_mul_f32_e32 v79, v85, v3
	v_fmac_f32_e32 v19, v28, v16
	v_fmac_f32_e32 v20, v40, v10
	v_add_f32_e32 v82, 0, v91
	v_fmac_f32_e32 v79, v84, v2
	v_fmac_f32_e32 v19, v29, v17
	v_fmac_f32_e32 v20, v30, v12
	v_add_f32_e32 v80, v82, v83
	v_fmac_f32_e32 v79, v76, v4
	v_add_f32_e32 v19, 0, v19
	v_fmac_f32_e32 v20, v31, v13
	v_add_f32_e32 v78, v80, v81
	v_fmac_f32_e32 v79, v77, v5
	v_mul_f32_e32 v77, v103, v15
	v_add_f32_e32 v19, v19, v20
	v_mul_f32_e32 v20, v37, v7
	v_add_f32_e32 v76, v78, v79
	v_fmac_f32_e32 v77, v102, v14
	v_mul_f32_e32 v78, v101, v11
	v_fmac_f32_e32 v20, v36, v6
	v_fmac_f32_e32 v77, v96, v16
	v_fmac_f32_e32 v78, v100, v10
	v_fmac_f32_e32 v20, v32, v8
	v_fmac_f32_e32 v77, v97, v17
	v_fmac_f32_e32 v78, v94, v12
	v_fmac_f32_e32 v20, v33, v9
	v_mul_f32_e32 v15, v43, v15
	v_add_f32_e32 v77, 0, v77
	v_fmac_f32_e32 v78, v95, v13
	v_add_f32_e32 v19, v19, v20
	v_mul_f32_e32 v20, v25, v3
	v_fmac_f32_e32 v15, v42, v14
	v_mul_f32_e32 v11, v49, v11
	v_mul_f32_e32 v3, v53, v3
	v_add_f32_e32 v77, v77, v78
	v_mul_f32_e32 v78, v99, v7
	v_fmac_f32_e32 v20, v24, v2
	v_fmac_f32_e32 v15, v38, v16
	v_fmac_f32_e32 v11, v48, v10
	v_mul_f32_e32 v7, v57, v7
	v_fmac_f32_e32 v3, v52, v2
	v_cndmask_b32_e32 v2, v59, v60, vcc
	v_fmac_f32_e32 v15, v39, v17
	v_fmac_f32_e32 v11, v44, v12
	v_fmac_f32_e32 v7, v56, v6
	ds_bpermute_b32 v2, v116, v2
	v_add_f32_e32 v14, 0, v15
	v_fmac_f32_e32 v11, v45, v13
	v_fmac_f32_e32 v7, v50, v8
	v_add_f32_e32 v10, v14, v11
	v_fmac_f32_e32 v7, v51, v9
	v_fmac_f32_e32 v3, v46, v4
	v_fmac_f32_e32 v78, v98, v6
	v_add_f32_e32 v6, v10, v7
	v_fmac_f32_e32 v3, v47, v5
	v_add_f32_e32 v7, v6, v3
	v_cndmask_b32_e32 v3, v60, v59, vcc
	v_fmac_f32_e32 v78, v92, v8
	s_waitcnt lgkmcnt(0)
	v_add_f32_e32 v8, v3, v2
	v_cndmask_b32_e32 v3, v62, v64, vcc
	v_fmac_f32_e32 v20, v22, v4
	ds_bpermute_b32 v3, v116, v3
	v_cndmask_b32_e32 v4, v65, v67, vcc
	v_fmac_f32_e32 v20, v23, v5
	ds_bpermute_b32 v4, v116, v4
	v_cndmask_b32_e32 v5, v104, v107, vcc
	ds_bpermute_b32 v5, v116, v5
	v_cndmask_b32_e32 v2, v64, v62, vcc
	v_fmac_f32_e32 v78, v93, v9
	s_waitcnt lgkmcnt(2)
	v_add_f32_e32 v9, v2, v3
	v_cndmask_b32_e32 v2, v67, v65, vcc
	v_cndmask_b32_e32 v3, v108, v111, vcc
	s_waitcnt lgkmcnt(1)
	v_add_f32_e32 v10, v2, v4
	v_cndmask_b32_e32 v2, v107, v104, vcc
	ds_bpermute_b32 v3, v116, v3
	v_cndmask_b32_e32 v4, v118, v120, vcc
	s_waitcnt lgkmcnt(1)
	v_add_f32_e32 v11, v2, v5
	ds_bpermute_b32 v4, v116, v4
	v_cndmask_b32_e32 v5, v122, v125, vcc
	ds_bpermute_b32 v5, v116, v5
	v_cndmask_b32_e32 v2, v111, v108, vcc
	s_waitcnt lgkmcnt(2)
	v_add_f32_e32 v12, v2, v3
	v_cndmask_b32_e32 v2, v120, v118, vcc
	v_cndmask_b32_e32 v3, v126, v129, vcc
	s_waitcnt lgkmcnt(1)
	v_add_f32_e32 v13, v2, v4
	v_cndmask_b32_e32 v2, v125, v122, vcc
	ds_bpermute_b32 v3, v116, v3
	v_cndmask_b32_e32 v4, v130, v132, vcc
	s_waitcnt lgkmcnt(1)
	v_add_f32_e32 v14, v2, v5
	ds_bpermute_b32 v4, v116, v4
	v_cndmask_b32_e32 v5, v134, v137, vcc
	ds_bpermute_b32 v5, v116, v5
	v_cndmask_b32_e32 v2, v129, v126, vcc
	s_waitcnt lgkmcnt(2)
	v_add_f32_e32 v15, v2, v3
	v_cndmask_b32_e32 v2, v132, v130, vcc
	v_cndmask_b32_e32 v3, v138, v141, vcc
	s_waitcnt lgkmcnt(1)
	v_add_f32_e32 v16, v2, v4
	v_cndmask_b32_e32 v2, v137, v134, vcc
	ds_bpermute_b32 v3, v116, v3
	v_cndmask_b32_e32 v4, v142, v144, vcc
	s_waitcnt lgkmcnt(1)
	v_add_f32_e32 v17, v2, v5
	ds_bpermute_b32 v4, v116, v4
	v_cndmask_b32_e32 v5, v146, v149, vcc
	ds_bpermute_b32 v5, v116, v5
	v_cndmask_b32_e32 v2, v141, v138, vcc
	v_add_f32_e32 v19, v19, v20
	s_waitcnt lgkmcnt(2)
	v_add_f32_e32 v20, v2, v3
	v_cndmask_b32_e32 v2, v144, v142, vcc
	s_waitcnt lgkmcnt(1)
	v_add_f32_e32 v3, v2, v4
	v_cndmask_b32_e32 v2, v149, v146, vcc
	s_waitcnt lgkmcnt(0)
	v_add_f32_e32 v2, v2, v5
	v_cndmask_b32_e32 v5, v150, v153, vcc
	v_add_f32_e32 v77, v77, v78
	ds_bpermute_b32 v5, v116, v5
	v_cndmask_b32_e32 v6, v154, v156, vcc
	v_add_f32_e32 v18, v77, v21
	ds_bpermute_b32 v6, v116, v6
	v_cndmask_b32_e32 v21, v76, v19, vcc
	ds_bpermute_b32 v21, v116, v21
	v_cndmask_b32_e32 v4, v153, v150, vcc
	s_waitcnt lgkmcnt(2)
	v_add_f32_e32 v5, v4, v5
	v_cndmask_b32_e32 v4, v156, v154, vcc
	s_waitcnt lgkmcnt(1)
	v_add_f32_e32 v4, v4, v6
	v_cndmask_b32_e32 v6, v19, v76, vcc
	s_waitcnt lgkmcnt(0)
	v_add_f32_e32 v6, v6, v21
	v_cndmask_b32_e32 v21, v54, v55, vcc
	ds_bpermute_b32 v21, v116, v21
	v_cndmask_b32_e32 v22, v58, v61, vcc
	ds_bpermute_b32 v22, v116, v22
	v_cndmask_b32_e32 v23, v63, v66, vcc
	ds_bpermute_b32 v23, v116, v23
	v_cndmask_b32_e32 v24, v75, v105, vcc
	ds_bpermute_b32 v24, v116, v24
	v_cndmask_b32_e32 v25, v106, v109, vcc
	v_cndmask_b32_e32 v19, v55, v54, vcc
	ds_bpermute_b32 v25, v116, v25
	v_cndmask_b32_e32 v28, v110, v119, vcc
	s_waitcnt lgkmcnt(4)
	v_add_f32_e32 v19, v19, v21
	v_cndmask_b32_e32 v21, v61, v58, vcc
	ds_bpermute_b32 v28, v116, v28
	v_cndmask_b32_e32 v29, v121, v123, vcc
	s_waitcnt lgkmcnt(4)
	v_add_f32_e32 v21, v21, v22
	v_cndmask_b32_e32 v22, v66, v63, vcc
	ds_bpermute_b32 v29, v116, v29
	v_cndmask_b32_e32 v30, v124, v127, vcc
	s_waitcnt lgkmcnt(4)
	v_add_f32_e32 v22, v22, v23
	v_cndmask_b32_e32 v23, v105, v75, vcc
	ds_bpermute_b32 v30, v116, v30
	v_cndmask_b32_e32 v31, v128, v131, vcc
	s_waitcnt lgkmcnt(4)
	v_add_f32_e32 v23, v23, v24
	v_cndmask_b32_e32 v24, v109, v106, vcc
	ds_bpermute_b32 v31, v116, v31
	v_cndmask_b32_e32 v32, v133, v135, vcc
	s_waitcnt lgkmcnt(4)
	v_add_f32_e32 v24, v24, v25
	v_cndmask_b32_e32 v25, v119, v110, vcc
	ds_bpermute_b32 v32, v116, v32
	v_cndmask_b32_e32 v33, v136, v139, vcc
	s_waitcnt lgkmcnt(4)
	v_add_f32_e32 v25, v25, v28
	v_cndmask_b32_e32 v28, v123, v121, vcc
	ds_bpermute_b32 v33, v116, v33
	v_cndmask_b32_e32 v34, v140, v143, vcc
	s_waitcnt lgkmcnt(4)
	v_add_f32_e32 v28, v28, v29
	v_cndmask_b32_e32 v29, v127, v124, vcc
	ds_bpermute_b32 v34, v116, v34
	v_cndmask_b32_e32 v35, v145, v147, vcc
	s_waitcnt lgkmcnt(4)
	v_add_f32_e32 v29, v29, v30
	v_cndmask_b32_e32 v30, v131, v128, vcc
	ds_bpermute_b32 v35, v116, v35
	v_cndmask_b32_e32 v36, v148, v151, vcc
	s_waitcnt lgkmcnt(4)
	v_add_f32_e32 v30, v30, v31
	v_cndmask_b32_e32 v31, v135, v133, vcc
	ds_bpermute_b32 v36, v116, v36
	v_cndmask_b32_e32 v37, v152, v155, vcc
	s_waitcnt lgkmcnt(4)
	v_add_f32_e32 v31, v31, v32
	v_cndmask_b32_e32 v32, v139, v136, vcc
	ds_bpermute_b32 v37, v116, v37
	s_waitcnt lgkmcnt(4)
	v_add_f32_e32 v32, v32, v33
	v_cndmask_b32_e32 v33, v143, v140, vcc
	s_waitcnt lgkmcnt(3)
	v_add_f32_e32 v33, v33, v34
	v_cndmask_b32_e32 v34, v147, v145, vcc
	s_waitcnt lgkmcnt(2)
	v_add_f32_e32 v34, v34, v35
	v_cndmask_b32_e32 v35, v151, v148, vcc
	s_waitcnt lgkmcnt(1)
	v_add_f32_e32 v35, v35, v36
	v_cndmask_b32_e32 v36, v155, v152, vcc
	s_waitcnt lgkmcnt(0)
	v_add_f32_e32 v36, v36, v37
	v_cndmask_b32_e32 v37, v7, v18, vcc
	v_cndmask_b32_e32 v7, v18, v7, vcc
	v_cndmask_b32_e64 v18, v8, v19, s[4:5]
	ds_bpermute_b32 v18, v115, v18
	v_cndmask_b32_e64 v8, v19, v8, s[4:5]
	v_cndmask_b32_e64 v38, v9, v21, s[4:5]
	v_cndmask_b32_e64 v9, v21, v9, s[4:5]
	v_cndmask_b32_e64 v21, v12, v24, s[4:5]
	s_waitcnt lgkmcnt(0)
	v_add_f32_e32 v8, v8, v18
	v_cndmask_b32_e64 v18, v22, v10, s[4:5]
	v_cndmask_b32_e64 v10, v10, v22, s[4:5]
	ds_bpermute_b32 v10, v115, v10
	ds_bpermute_b32 v21, v115, v21
	v_cndmask_b32_e64 v12, v24, v12, s[4:5]
	s_load_dwordx2 s[0:1], s[0:1], 0x68
	v_cndmask_b32_e64 v19, v11, v23, s[4:5]
	s_waitcnt lgkmcnt(0)
	v_add_f32_e32 v10, v18, v10
	v_cndmask_b32_e64 v18, v25, v13, s[4:5]
	v_cndmask_b32_e64 v13, v13, v25, s[4:5]
	v_add_f32_e32 v12, v12, v21
	ds_bpermute_b32 v13, v115, v13
	v_cndmask_b32_e64 v21, v15, v29, s[4:5]
	ds_bpermute_b32 v21, v115, v21
	v_cndmask_b32_e64 v15, v29, v15, s[4:5]
	ds_bpermute_b32 v19, v115, v19
	s_waitcnt lgkmcnt(2)
	v_add_f32_e32 v13, v18, v13
	v_cndmask_b32_e64 v18, v30, v16, s[4:5]
	v_cndmask_b32_e64 v16, v16, v30, s[4:5]
	s_waitcnt lgkmcnt(1)
	v_add_f32_e32 v15, v15, v21
	ds_bpermute_b32 v16, v115, v16
	v_cndmask_b32_e64 v21, v20, v32, s[4:5]
	ds_bpermute_b32 v21, v115, v21
	v_cndmask_b32_e64 v11, v23, v11, s[4:5]
	s_waitcnt lgkmcnt(2)
	v_add_f32_e32 v11, v11, v19
	s_waitcnt lgkmcnt(1)
	v_add_f32_e32 v16, v18, v16
	v_cndmask_b32_e64 v18, v32, v20, s[4:5]
	s_waitcnt lgkmcnt(0)
	v_add_f32_e32 v18, v18, v21
	global_load_dword v21, v69, s[0:1]
	v_cndmask_b32_e64 v19, v14, v28, s[4:5]
	ds_bpermute_b32 v19, v115, v19
	v_cndmask_b32_e64 v14, v28, v14, s[4:5]
	ds_bpermute_b32 v7, v116, v7
	v_cndmask_b32_e64 v20, v2, v34, s[4:5]
	ds_bpermute_b32 v38, v115, v38
	s_waitcnt lgkmcnt(2)
	v_add_f32_e32 v14, v14, v19
	v_cndmask_b32_e64 v19, v17, v31, s[4:5]
	ds_bpermute_b32 v19, v115, v19
	v_cndmask_b32_e64 v17, v31, v17, s[4:5]
	s_waitcnt lgkmcnt(2)
	v_add_f32_e32 v7, v37, v7
	ds_bpermute_b32 v20, v115, v20
	v_cndmask_b32_e64 v22, v6, v7, s[4:5]
	s_waitcnt lgkmcnt(1)
	v_add_f32_e32 v17, v17, v19
	v_cndmask_b32_e64 v19, v3, v33, s[4:5]
	ds_bpermute_b32 v19, v115, v19
	v_cndmask_b32_e64 v3, v33, v3, s[4:5]
	v_cndmask_b32_e64 v6, v7, v6, s[4:5]
	v_cndmask_b32_e64 v7, v16, v8, s[6:7]
	v_cndmask_b32_e64 v8, v8, v16, s[6:7]
	s_waitcnt lgkmcnt(0)
	v_add_f32_e32 v3, v3, v19
	v_cndmask_b32_e64 v19, v35, v5, s[4:5]
	v_cndmask_b32_e64 v5, v5, v35, s[4:5]
	ds_bpermute_b32 v5, v115, v5
	ds_bpermute_b32 v8, v114, v8
	v_cndmask_b32_e64 v2, v34, v2, s[4:5]
	v_add_f32_e32 v9, v9, v38
	v_add_f32_e32 v2, v2, v20
	v_cndmask_b32_e64 v20, v4, v36, s[4:5]
	ds_bpermute_b32 v20, v115, v20
	ds_bpermute_b32 v22, v115, v22
	s_waitcnt lgkmcnt(3)
	v_add_f32_e32 v5, v19, v5
	v_cndmask_b32_e64 v16, v9, v17, s[6:7]
	v_cndmask_b32_e64 v19, v10, v18, s[6:7]
	s_waitcnt lgkmcnt(2)
	v_add_f32_e32 v7, v7, v8
	v_cndmask_b32_e64 v8, v17, v9, s[6:7]
	v_cndmask_b32_e64 v9, v18, v10, s[6:7]
	v_cndmask_b32_e64 v10, v3, v11, s[6:7]
	v_cndmask_b32_e64 v3, v11, v3, s[6:7]
	v_cndmask_b32_e64 v11, v12, v2, s[6:7]
	ds_bpermute_b32 v16, v114, v16
	ds_bpermute_b32 v3, v114, v3
	ds_bpermute_b32 v11, v114, v11
	v_cndmask_b32_e64 v4, v36, v4, s[4:5]
	s_waitcnt lgkmcnt(4)
	v_add_f32_e32 v4, v4, v20
	s_waitcnt lgkmcnt(3)
	v_add_f32_e32 v6, v6, v22
	v_cndmask_b32_e64 v2, v2, v12, s[6:7]
	s_waitcnt lgkmcnt(2)
	v_add_f32_e32 v8, v8, v16
	v_cndmask_b32_e64 v16, v13, v5, s[6:7]
	s_waitcnt lgkmcnt(1)
	v_add_f32_e32 v3, v10, v3
	s_waitcnt lgkmcnt(0)
	v_add_f32_e32 v2, v2, v11
	v_cndmask_b32_e64 v10, v4, v14, s[6:7]
	v_cndmask_b32_e64 v4, v14, v4, s[6:7]
	v_cndmask_b32_e64 v11, v15, v6, s[6:7]
	ds_bpermute_b32 v19, v114, v19
	ds_bpermute_b32 v16, v114, v16
	ds_bpermute_b32 v4, v114, v4
	ds_bpermute_b32 v11, v114, v11
	v_cndmask_b32_e64 v5, v5, v13, s[6:7]
	v_cndmask_b32_e64 v6, v6, v15, s[6:7]
	s_waitcnt lgkmcnt(3)
	v_add_f32_e32 v9, v9, v19
	s_waitcnt lgkmcnt(2)
	v_add_f32_e32 v5, v5, v16
	s_waitcnt lgkmcnt(1)
	v_add_f32_e32 v4, v10, v4
	s_waitcnt lgkmcnt(0)
	v_add_f32_e32 v6, v6, v11
	v_cndmask_b32_e64 v12, v7, v2, s[8:9]
	v_cndmask_b32_e64 v2, v2, v7, s[8:9]
	v_cndmask_b32_e64 v7, v5, v8, s[8:9]
	v_cndmask_b32_e64 v5, v8, v5, s[8:9]
	v_cndmask_b32_e64 v8, v9, v4, s[8:9]
	v_cndmask_b32_e64 v10, v3, v6, s[8:9]
	ds_bpermute_b32 v12, v113, v12
	ds_bpermute_b32 v5, v113, v5
	ds_bpermute_b32 v8, v113, v8
	ds_bpermute_b32 v10, v113, v10
	v_cndmask_b32_e64 v4, v4, v9, s[8:9]
	v_cndmask_b32_e64 v3, v6, v3, s[8:9]
	s_waitcnt lgkmcnt(3)
	v_add_f32_e32 v2, v2, v12
	s_waitcnt lgkmcnt(2)
	v_add_f32_e32 v5, v7, v5
	s_waitcnt lgkmcnt(1)
	v_add_f32_e32 v4, v4, v8
	s_waitcnt lgkmcnt(0)
	v_add_f32_e32 v3, v3, v10
	v_cndmask_b32_e64 v6, v2, v4, s[10:11]
	v_cndmask_b32_e64 v7, v5, v3, s[10:11]
	ds_bpermute_b32 v6, v112, v6
	ds_bpermute_b32 v7, v112, v7
	v_cndmask_b32_e64 v2, v4, v2, s[10:11]
	v_cndmask_b32_e64 v3, v3, v5, s[10:11]
	s_mov_b32 s0, 0xbfb8aa3b
	s_waitcnt lgkmcnt(1)
	v_add_f32_e32 v2, v2, v6
	s_waitcnt lgkmcnt(0)
	v_add_f32_e32 v3, v3, v7
	v_cndmask_b32_e64 v4, v2, v3, s[12:13]
	ds_bpermute_b32 v4, v27, v4
	v_cndmask_b32_e64 v2, v3, v2, s[12:13]
	s_waitcnt lgkmcnt(0)
	v_add_f32_e32 v2, v2, v4
	s_waitcnt vmcnt(0)
	v_add_f32_e32 v2, v21, v2
	v_mul_f32_e64 v3, |v2|, s0
	v_exp_f32_e32 v4, v3
	s_mov_b32 s0, 0x3cf5c28f
	v_cmp_ngt_f32_e64 s[0:1], s0, v4
	s_and_saveexec_b64 s[2:3], s[0:1]
	s_xor_b64 s[26:27], exec, s[2:3]
	s_cbranch_execz .LBB0_504
	v_add_f32_e32 v3, 1.0, v4
	s_mov_b32 s0, 0x800000
	v_cmp_gt_f32_e64 s[0:1], s0, v3
	s_mov_b32 s2, 0x3f317217
	s_nop 0
	v_cndmask_b32_e64 v4, 0, 32, s[0:1]
	v_ldexp_f32 v3, v3, v4
	v_log_f32_e32 v3, v3
	s_nop 0
	v_mul_f32_e32 v4, 0x3f317217, v3
	v_fma_f32 v4, v3, s2, -v4
	v_fmac_f32_e32 v4, 0x3377d1cf, v3
	s_mov_b32 s2, 0x7f800000
	v_fmac_f32_e32 v4, 0x3f317217, v3
	v_cmp_lt_f32_e64 s[2:3], |v3|, s2
	s_nop 1
	v_cndmask_b32_e64 v3, v3, v4, s[2:3]
	v_mov_b32_e32 v4, 0x41b17218
	v_cndmask_b32_e64 v4, 0, v4, s[0:1]
	v_sub_f32_e32 v3, v3, v4
